# v17: v16 + P6b lane-bit-0 Hadamard stage as 4 xor then 4 add_dpp (86 s_nop per row removed; P6b is VALU-issue bound)
# baseline (speedup 1.0000x reference)
.LBB0_909:
	s_waitcnt lgkmcnt(0)
	v_lshl_add_u64 v[4:5], s[8:9], 0, v[2:3]
	v_add_co_u32_e32 v24, vcc, 0x23000000, v4
	s_nop 1
	v_addc_co_u32_e32 v25, vcc, 0, v5, vcc
	global_load_dwordx2 v[86:87], v[24:25], off nt
	v_add_co_u32_e32 v54, vcc, s24, v4
	s_nop 1
	v_addc_co_u32_e32 v55, vcc, 0, v5, vcc
	v_add_co_u32_e32 v88, vcc, s25, v4
	s_nop 1
	v_addc_co_u32_e32 v89, vcc, 0, v5, vcc
	v_add_co_u32_e32 v90, vcc, s26, v4
	s_nop 1
	v_addc_co_u32_e32 v91, vcc, 0, v5, vcc
	global_load_dwordx2 v[36:37], v[54:55], off offset:1024 nt
	global_load_dwordx2 v[34:35], v[54:55], off offset:1536 nt
	global_load_dwordx2 v[32:33], v[54:55], off offset:2048 nt
	global_load_dwordx2 v[30:31], v[54:55], off offset:2560 nt
	global_load_dwordx2 v[22:23], v[88:89], off offset:512 nt
	global_load_dwordx2 v[20:21], v[88:89], off offset:1024 nt
	global_load_dwordx2 v[18:19], v[88:89], off offset:1536 nt
	global_load_dwordx2 v[16:17], v[88:89], off offset:2048 nt
	global_load_dwordx2 v[14:15], v[88:89], off offset:2560 nt
	global_load_dwordx2 v[12:13], v[88:89], off offset:3072 nt
	global_load_dwordx2 v[10:11], v[88:89], off offset:3584 nt
	global_load_dwordx2 v[28:29], v[54:55], off offset:3072 nt
	global_load_dwordx2 v[26:27], v[54:55], off offset:3584 nt
	global_load_dwordx2 v[8:9], v[90:91], off nt
	global_load_dwordx2 v[6:7], v[90:91], off offset:512 nt
	global_load_dwordx2 v[92:93], v[24:25], off offset:512 nt
	global_load_dwordx2 v[94:95], v[24:25], off offset:1024 nt
	global_load_dwordx2 v[96:97], v[24:25], off offset:1536 nt
	global_load_dwordx2 v[80:81], v[24:25], off offset:2048 nt
	global_load_dwordx2 v[78:79], v[24:25], off offset:2560 nt
	global_load_dwordx2 v[76:77], v[24:25], off offset:3072 nt
	global_load_dwordx2 v[74:75], v[24:25], off offset:3584 nt
	v_add_co_u32_e32 v56, vcc, s22, v4
	s_nop 1
	v_addc_co_u32_e32 v57, vcc, 0, v5, vcc
	v_add_co_u32_e32 v98, vcc, s23, v4
	s_nop 1
	v_addc_co_u32_e32 v99, vcc, 0, v5, vcc
	global_load_dwordx2 v[70:71], v[56:57], off offset:512 nt
	global_load_dwordx2 v[68:69], v[56:57], off offset:1024 nt
	global_load_dwordx2 v[66:67], v[56:57], off offset:1536 nt
	global_load_dwordx2 v[64:65], v[56:57], off offset:2048 nt
	global_load_dwordx2 v[62:63], v[56:57], off offset:2560 nt
	global_load_dwordx2 v[60:61], v[56:57], off offset:3072 nt
	global_load_dwordx2 v[58:59], v[56:57], off offset:3584 nt
	global_load_dwordx2 v[38:39], v[54:55], off offset:512 nt
	global_load_dwordx2 v[52:53], v[98:99], off offset:1024 nt
	global_load_dwordx2 v[50:51], v[98:99], off offset:1536 nt
	global_load_dwordx2 v[48:49], v[98:99], off offset:2048 nt
	global_load_dwordx2 v[46:47], v[98:99], off offset:2560 nt
	global_load_dwordx2 v[44:45], v[98:99], off offset:3072 nt
	global_load_dwordx2 v[42:43], v[98:99], off offset:3584 nt
	global_load_dwordx2 v[40:41], v[88:89], off offset:-4096 nt
	global_load_dwordx2 v[24:25], v[88:89], off nt
	global_load_dwordx2 v[72:73], v[98:99], off offset:-4096 nt
	global_load_dwordx2 v[56:57], v[98:99], off nt
	global_load_dwordx2 v[54:55], v[98:99], off offset:512 nt
	global_load_dwordx2 v[4:5], v[90:91], off offset:1024 nt
	s_waitcnt vmcnt(42)
	v_lshlrev_b32_e32 v88, 16, v86
	v_and_b32_e32 v86, 0xffff0000, v86
	v_lshlrev_b32_e32 v89, 16, v87
	v_and_b32_e32 v87, 0xffff0000, v87
	v_add_f32_e32 v90, v88, v86
	v_sub_f32_e32 v86, v88, v86
	v_add_f32_e32 v88, v89, v87
	v_sub_f32_e32 v87, v89, v87
	v_add_f32_e32 v89, v90, v88
	v_add_f32_e32 v91, v86, v87
	v_sub_f32_e32 v88, v90, v88
	v_sub_f32_e32 v86, v86, v87
	v_xor_b32_e32 v204, v82, v89
	v_xor_b32_e32 v205, v82, v91
	v_xor_b32_e32 v206, v82, v88
	v_xor_b32_e32 v207, v82, v86
	v_add_f32_dpp v87, v89, v204 quad_perm:[1,0,3,2] row_mask:0xf bank_mask:0xf bound_ctrl:1
	v_add_f32_dpp v89, v91, v205 quad_perm:[1,0,3,2] row_mask:0xf bank_mask:0xf bound_ctrl:1
	v_add_f32_dpp v88, v88, v206 quad_perm:[1,0,3,2] row_mask:0xf bank_mask:0xf bound_ctrl:1
	v_add_f32_dpp v86, v86, v207 quad_perm:[1,0,3,2] row_mask:0xf bank_mask:0xf bound_ctrl:1
	v_xor_b32_e32 v200, v83, v87
	v_xor_b32_e32 v201, v83, v89
	v_xor_b32_e32 v202, v83, v88
	v_xor_b32_e32 v203, v83, v86
	v_add_f32_dpp v204, v87, v200 quad_perm:[2,3,0,1] row_mask:0xf bank_mask:0xf bound_ctrl:1
	v_add_f32_dpp v205, v89, v201 quad_perm:[2,3,0,1] row_mask:0xf bank_mask:0xf bound_ctrl:1
	v_add_f32_dpp v206, v88, v202 quad_perm:[2,3,0,1] row_mask:0xf bank_mask:0xf bound_ctrl:1
	v_add_f32_dpp v207, v86, v203 quad_perm:[2,3,0,1] row_mask:0xf bank_mask:0xf bound_ctrl:1
	v_xor_b32_e32 v200, v84, v204
	v_xor_b32_e32 v201, v84, v205
	v_xor_b32_e32 v202, v84, v206
	v_xor_b32_e32 v203, v84, v207
	v_add_f32_dpp v87, v204, v200 row_shl:4 row_mask:0xf bank_mask:0x5
	v_add_f32_dpp v89, v205, v201 row_shl:4 row_mask:0xf bank_mask:0x5
	v_add_f32_dpp v88, v206, v202 row_shl:4 row_mask:0xf bank_mask:0x5
	v_add_f32_dpp v90, v207, v203 row_shl:4 row_mask:0xf bank_mask:0x5
	v_add_f32_dpp v87, v204, v200 row_shr:4 row_mask:0xf bank_mask:0xa
	v_add_f32_dpp v89, v205, v201 row_shr:4 row_mask:0xf bank_mask:0xa
	v_add_f32_dpp v88, v206, v202 row_shr:4 row_mask:0xf bank_mask:0xa
	v_add_f32_dpp v90, v207, v203 row_shr:4 row_mask:0xf bank_mask:0xa
	v_max_f32_e64 v86, |v87|, |v89|
	v_max_f32_e64 v91, |v88|, |v90|
	v_max3_f32 v91, v86, 0, v91
	v_cvt_pk_bf16_f32 v86, v87, v89
	v_cvt_pk_bf16_f32 v87, v88, v90
	s_waitcnt vmcnt(26)
	v_lshlrev_b32_e32 v88, 16, v92
	v_and_b32_e32 v89, 0xffff0000, v92
	v_lshlrev_b32_e32 v90, 16, v93
	v_and_b32_e32 v92, 0xffff0000, v93
	v_add_f32_e32 v93, v88, v89
	v_sub_f32_e32 v88, v88, v89
	v_add_f32_e32 v89, v90, v92
	v_sub_f32_e32 v90, v90, v92
	v_add_f32_e32 v92, v93, v89
	v_sub_f32_e32 v89, v93, v89
	v_add_f32_e32 v98, v88, v90
	v_sub_f32_e32 v88, v88, v90
	v_xor_b32_e32 v204, v82, v92
	v_xor_b32_e32 v205, v82, v89
	v_xor_b32_e32 v206, v82, v98
	v_xor_b32_e32 v207, v82, v88
	v_add_f32_dpp v90, v92, v204 quad_perm:[1,0,3,2] row_mask:0xf bank_mask:0xf bound_ctrl:1
	v_add_f32_dpp v89, v89, v205 quad_perm:[1,0,3,2] row_mask:0xf bank_mask:0xf bound_ctrl:1
	v_add_f32_dpp v92, v98, v206 quad_perm:[1,0,3,2] row_mask:0xf bank_mask:0xf bound_ctrl:1
	v_add_f32_dpp v88, v88, v207 quad_perm:[1,0,3,2] row_mask:0xf bank_mask:0xf bound_ctrl:1
	v_xor_b32_e32 v200, v83, v90
	v_xor_b32_e32 v201, v83, v92
	v_xor_b32_e32 v202, v83, v89
	v_xor_b32_e32 v203, v83, v88
	v_add_f32_dpp v204, v90, v200 quad_perm:[2,3,0,1] row_mask:0xf bank_mask:0xf bound_ctrl:1
	v_add_f32_dpp v205, v92, v201 quad_perm:[2,3,0,1] row_mask:0xf bank_mask:0xf bound_ctrl:1
	v_add_f32_dpp v206, v89, v202 quad_perm:[2,3,0,1] row_mask:0xf bank_mask:0xf bound_ctrl:1
	v_add_f32_dpp v207, v88, v203 quad_perm:[2,3,0,1] row_mask:0xf bank_mask:0xf bound_ctrl:1
	v_xor_b32_e32 v200, v84, v204
	v_xor_b32_e32 v201, v84, v205
	v_xor_b32_e32 v202, v84, v206
	v_xor_b32_e32 v203, v84, v207
	v_add_f32_dpp v90, v204, v200 row_shl:4 row_mask:0xf bank_mask:0x5
	v_add_f32_dpp v92, v205, v201 row_shl:4 row_mask:0xf bank_mask:0x5
	v_add_f32_dpp v89, v206, v202 row_shl:4 row_mask:0xf bank_mask:0x5
	v_add_f32_dpp v93, v207, v203 row_shl:4 row_mask:0xf bank_mask:0x5
	v_add_f32_dpp v90, v204, v200 row_shr:4 row_mask:0xf bank_mask:0xa
	v_add_f32_dpp v92, v205, v201 row_shr:4 row_mask:0xf bank_mask:0xa
	v_add_f32_dpp v89, v206, v202 row_shr:4 row_mask:0xf bank_mask:0xa
	v_add_f32_dpp v93, v207, v203 row_shr:4 row_mask:0xf bank_mask:0xa
	v_max_f32_e64 v88, |v90|, |v92|
	v_max_f32_e64 v98, |v89|, |v93|
	v_max3_f32 v91, v91, v88, v98
	v_cvt_pk_bf16_f32 v88, v90, v92
	v_cvt_pk_bf16_f32 v89, v89, v93
	s_waitcnt vmcnt(25)
	v_lshlrev_b32_e32 v90, 16, v94
	v_and_b32_e32 v92, 0xffff0000, v94
	v_lshlrev_b32_e32 v93, 16, v95
	v_and_b32_e32 v94, 0xffff0000, v95
	v_add_f32_e32 v95, v90, v92
	v_sub_f32_e32 v90, v90, v92
	v_add_f32_e32 v92, v93, v94
	v_sub_f32_e32 v93, v93, v94
	v_add_f32_e32 v94, v95, v92
	v_sub_f32_e32 v92, v95, v92
	v_add_f32_e32 v98, v90, v93
	v_sub_f32_e32 v90, v90, v93
	v_xor_b32_e32 v204, v82, v94
	v_xor_b32_e32 v205, v82, v92
	v_xor_b32_e32 v206, v82, v98
	v_xor_b32_e32 v207, v82, v90
	v_add_f32_dpp v93, v94, v204 quad_perm:[1,0,3,2] row_mask:0xf bank_mask:0xf bound_ctrl:1
	v_add_f32_dpp v92, v92, v205 quad_perm:[1,0,3,2] row_mask:0xf bank_mask:0xf bound_ctrl:1
	v_add_f32_dpp v94, v98, v206 quad_perm:[1,0,3,2] row_mask:0xf bank_mask:0xf bound_ctrl:1
	v_add_f32_dpp v90, v90, v207 quad_perm:[1,0,3,2] row_mask:0xf bank_mask:0xf bound_ctrl:1
	v_xor_b32_e32 v200, v83, v93
	v_xor_b32_e32 v201, v83, v94
	v_xor_b32_e32 v202, v83, v92
	v_xor_b32_e32 v203, v83, v90
	v_add_f32_dpp v204, v93, v200 quad_perm:[2,3,0,1] row_mask:0xf bank_mask:0xf bound_ctrl:1
	v_add_f32_dpp v205, v94, v201 quad_perm:[2,3,0,1] row_mask:0xf bank_mask:0xf bound_ctrl:1
	v_add_f32_dpp v206, v92, v202 quad_perm:[2,3,0,1] row_mask:0xf bank_mask:0xf bound_ctrl:1
	v_add_f32_dpp v207, v90, v203 quad_perm:[2,3,0,1] row_mask:0xf bank_mask:0xf bound_ctrl:1
	v_xor_b32_e32 v200, v84, v204
	v_xor_b32_e32 v201, v84, v205
	v_xor_b32_e32 v202, v84, v206
	v_xor_b32_e32 v203, v84, v207
	v_add_f32_dpp v93, v204, v200 row_shl:4 row_mask:0xf bank_mask:0x5
	v_add_f32_dpp v94, v205, v201 row_shl:4 row_mask:0xf bank_mask:0x5
	v_add_f32_dpp v92, v206, v202 row_shl:4 row_mask:0xf bank_mask:0x5
	v_add_f32_dpp v95, v207, v203 row_shl:4 row_mask:0xf bank_mask:0x5
	v_add_f32_dpp v93, v204, v200 row_shr:4 row_mask:0xf bank_mask:0xa
	v_add_f32_dpp v94, v205, v201 row_shr:4 row_mask:0xf bank_mask:0xa
	v_add_f32_dpp v92, v206, v202 row_shr:4 row_mask:0xf bank_mask:0xa
	v_add_f32_dpp v95, v207, v203 row_shr:4 row_mask:0xf bank_mask:0xa
	v_max_f32_e64 v90, |v93|, |v94|
	v_max_f32_e64 v98, |v92|, |v95|
	v_max3_f32 v98, v91, v90, v98
	v_cvt_pk_bf16_f32 v90, v93, v94
	v_cvt_pk_bf16_f32 v91, v92, v95
	s_waitcnt vmcnt(24)
	v_lshlrev_b32_e32 v92, 16, v96
	v_and_b32_e32 v93, 0xffff0000, v96
	v_lshlrev_b32_e32 v94, 16, v97
	v_and_b32_e32 v95, 0xffff0000, v97
	v_add_f32_e32 v96, v92, v93
	v_sub_f32_e32 v92, v92, v93
	v_add_f32_e32 v93, v94, v95
	v_sub_f32_e32 v94, v94, v95
	v_add_f32_e32 v95, v96, v93
	v_sub_f32_e32 v93, v96, v93
	v_add_f32_e32 v97, v92, v94
	v_sub_f32_e32 v92, v92, v94
	v_xor_b32_e32 v204, v82, v95
	v_xor_b32_e32 v205, v82, v93
	v_xor_b32_e32 v206, v82, v97
	v_xor_b32_e32 v207, v82, v92
	v_add_f32_dpp v94, v95, v204 quad_perm:[1,0,3,2] row_mask:0xf bank_mask:0xf bound_ctrl:1
	v_add_f32_dpp v93, v93, v205 quad_perm:[1,0,3,2] row_mask:0xf bank_mask:0xf bound_ctrl:1
	v_add_f32_dpp v95, v97, v206 quad_perm:[1,0,3,2] row_mask:0xf bank_mask:0xf bound_ctrl:1
	v_add_f32_dpp v92, v92, v207 quad_perm:[1,0,3,2] row_mask:0xf bank_mask:0xf bound_ctrl:1
	v_xor_b32_e32 v200, v83, v94
	v_xor_b32_e32 v201, v83, v95
	v_xor_b32_e32 v202, v83, v93
	v_xor_b32_e32 v203, v83, v92
	v_add_f32_dpp v204, v94, v200 quad_perm:[2,3,0,1] row_mask:0xf bank_mask:0xf bound_ctrl:1
	v_add_f32_dpp v205, v95, v201 quad_perm:[2,3,0,1] row_mask:0xf bank_mask:0xf bound_ctrl:1
	v_add_f32_dpp v206, v93, v202 quad_perm:[2,3,0,1] row_mask:0xf bank_mask:0xf bound_ctrl:1
	v_add_f32_dpp v207, v92, v203 quad_perm:[2,3,0,1] row_mask:0xf bank_mask:0xf bound_ctrl:1
	v_xor_b32_e32 v200, v84, v204
	v_xor_b32_e32 v201, v84, v205
	v_xor_b32_e32 v202, v84, v206
	v_xor_b32_e32 v203, v84, v207
	v_add_f32_dpp v94, v204, v200 row_shl:4 row_mask:0xf bank_mask:0x5
	v_add_f32_dpp v95, v205, v201 row_shl:4 row_mask:0xf bank_mask:0x5
	v_add_f32_dpp v93, v206, v202 row_shl:4 row_mask:0xf bank_mask:0x5
	v_add_f32_dpp v96, v207, v203 row_shl:4 row_mask:0xf bank_mask:0x5
	v_add_f32_dpp v94, v204, v200 row_shr:4 row_mask:0xf bank_mask:0xa
	v_add_f32_dpp v95, v205, v201 row_shr:4 row_mask:0xf bank_mask:0xa
	v_add_f32_dpp v93, v206, v202 row_shr:4 row_mask:0xf bank_mask:0xa
	v_add_f32_dpp v96, v207, v203 row_shr:4 row_mask:0xf bank_mask:0xa
	v_max_f32_e64 v92, |v94|, |v95|
	v_max_f32_e64 v97, |v93|, |v96|
	v_max3_f32 v97, v98, v92, v97
	v_cvt_pk_bf16_f32 v92, v94, v95
	s_waitcnt vmcnt(23)
	v_lshlrev_b32_e32 v94, 16, v80
	v_and_b32_e32 v80, 0xffff0000, v80
	v_lshlrev_b32_e32 v95, 16, v81
	v_and_b32_e32 v81, 0xffff0000, v81
	v_cvt_pk_bf16_f32 v93, v93, v96
	v_add_f32_e32 v96, v94, v80
	v_sub_f32_e32 v80, v94, v80
	v_add_f32_e32 v94, v95, v81
	v_sub_f32_e32 v81, v95, v81
	v_add_f32_e32 v95, v96, v94
	v_sub_f32_e32 v94, v96, v94
	v_add_f32_e32 v98, v80, v81
	v_sub_f32_e32 v80, v80, v81
	v_xor_b32_e32 v204, v82, v95
	v_xor_b32_e32 v205, v82, v94
	v_xor_b32_e32 v206, v82, v98
	v_xor_b32_e32 v207, v82, v80
	v_add_f32_dpp v81, v95, v204 quad_perm:[1,0,3,2] row_mask:0xf bank_mask:0xf bound_ctrl:1
	v_add_f32_dpp v94, v94, v205 quad_perm:[1,0,3,2] row_mask:0xf bank_mask:0xf bound_ctrl:1
	v_add_f32_dpp v95, v98, v206 quad_perm:[1,0,3,2] row_mask:0xf bank_mask:0xf bound_ctrl:1
	v_add_f32_dpp v80, v80, v207 quad_perm:[1,0,3,2] row_mask:0xf bank_mask:0xf bound_ctrl:1
	v_xor_b32_e32 v200, v83, v81
	v_xor_b32_e32 v201, v83, v95
	v_xor_b32_e32 v202, v83, v94
	v_xor_b32_e32 v203, v83, v80
	v_add_f32_dpp v204, v81, v200 quad_perm:[2,3,0,1] row_mask:0xf bank_mask:0xf bound_ctrl:1
	v_add_f32_dpp v205, v95, v201 quad_perm:[2,3,0,1] row_mask:0xf bank_mask:0xf bound_ctrl:1
	v_add_f32_dpp v206, v94, v202 quad_perm:[2,3,0,1] row_mask:0xf bank_mask:0xf bound_ctrl:1
	v_add_f32_dpp v207, v80, v203 quad_perm:[2,3,0,1] row_mask:0xf bank_mask:0xf bound_ctrl:1
	v_xor_b32_e32 v200, v84, v204
	v_xor_b32_e32 v201, v84, v205
	v_xor_b32_e32 v202, v84, v206
	v_xor_b32_e32 v203, v84, v207
	v_add_f32_dpp v81, v204, v200 row_shl:4 row_mask:0xf bank_mask:0x5
	v_add_f32_dpp v95, v205, v201 row_shl:4 row_mask:0xf bank_mask:0x5
	v_add_f32_dpp v94, v206, v202 row_shl:4 row_mask:0xf bank_mask:0x5
	v_add_f32_dpp v96, v207, v203 row_shl:4 row_mask:0xf bank_mask:0x5
	v_add_f32_dpp v81, v204, v200 row_shr:4 row_mask:0xf bank_mask:0xa
	v_add_f32_dpp v95, v205, v201 row_shr:4 row_mask:0xf bank_mask:0xa
	v_add_f32_dpp v94, v206, v202 row_shr:4 row_mask:0xf bank_mask:0xa
	v_add_f32_dpp v96, v207, v203 row_shr:4 row_mask:0xf bank_mask:0xa
	v_max_f32_e64 v80, |v81|, |v95|
	v_max_f32_e64 v98, |v94|, |v96|
	v_max3_f32 v97, v97, v80, v98
	v_cvt_pk_bf16_f32 v80, v81, v95
	v_cvt_pk_bf16_f32 v81, v94, v96
	s_waitcnt vmcnt(22)
	v_lshlrev_b32_e32 v94, 16, v78
	v_and_b32_e32 v78, 0xffff0000, v78
	v_lshlrev_b32_e32 v95, 16, v79
	v_and_b32_e32 v79, 0xffff0000, v79
	v_add_f32_e32 v96, v94, v78
	v_sub_f32_e32 v78, v94, v78
	v_add_f32_e32 v94, v95, v79
	v_sub_f32_e32 v79, v95, v79
	v_add_f32_e32 v95, v96, v94
	v_sub_f32_e32 v94, v96, v94
	v_add_f32_e32 v98, v78, v79
	v_sub_f32_e32 v78, v78, v79
	v_xor_b32_e32 v204, v82, v95
	v_xor_b32_e32 v205, v82, v94
	v_xor_b32_e32 v206, v82, v98
	v_xor_b32_e32 v207, v82, v78
	v_add_f32_dpp v79, v95, v204 quad_perm:[1,0,3,2] row_mask:0xf bank_mask:0xf bound_ctrl:1
	v_add_f32_dpp v94, v94, v205 quad_perm:[1,0,3,2] row_mask:0xf bank_mask:0xf bound_ctrl:1
	v_add_f32_dpp v95, v98, v206 quad_perm:[1,0,3,2] row_mask:0xf bank_mask:0xf bound_ctrl:1
	v_add_f32_dpp v78, v78, v207 quad_perm:[1,0,3,2] row_mask:0xf bank_mask:0xf bound_ctrl:1
	v_xor_b32_e32 v200, v83, v79
	v_xor_b32_e32 v201, v83, v95
	v_xor_b32_e32 v202, v83, v94
	v_xor_b32_e32 v203, v83, v78
	v_add_f32_dpp v204, v79, v200 quad_perm:[2,3,0,1] row_mask:0xf bank_mask:0xf bound_ctrl:1
	v_add_f32_dpp v205, v95, v201 quad_perm:[2,3,0,1] row_mask:0xf bank_mask:0xf bound_ctrl:1
	v_add_f32_dpp v206, v94, v202 quad_perm:[2,3,0,1] row_mask:0xf bank_mask:0xf bound_ctrl:1
	v_add_f32_dpp v207, v78, v203 quad_perm:[2,3,0,1] row_mask:0xf bank_mask:0xf bound_ctrl:1
	v_xor_b32_e32 v200, v84, v204
	v_xor_b32_e32 v201, v84, v205
	v_xor_b32_e32 v202, v84, v206
	v_xor_b32_e32 v203, v84, v207
	v_add_f32_dpp v79, v204, v200 row_shl:4 row_mask:0xf bank_mask:0x5
	v_add_f32_dpp v95, v205, v201 row_shl:4 row_mask:0xf bank_mask:0x5
	v_add_f32_dpp v94, v206, v202 row_shl:4 row_mask:0xf bank_mask:0x5
	v_add_f32_dpp v96, v207, v203 row_shl:4 row_mask:0xf bank_mask:0x5
	v_add_f32_dpp v79, v204, v200 row_shr:4 row_mask:0xf bank_mask:0xa
	v_add_f32_dpp v95, v205, v201 row_shr:4 row_mask:0xf bank_mask:0xa
	v_add_f32_dpp v94, v206, v202 row_shr:4 row_mask:0xf bank_mask:0xa
	v_add_f32_dpp v96, v207, v203 row_shr:4 row_mask:0xf bank_mask:0xa
	v_max_f32_e64 v78, |v79|, |v95|
	v_max_f32_e64 v98, |v94|, |v96|
	v_max3_f32 v97, v97, v78, v98
	v_cvt_pk_bf16_f32 v78, v79, v95
	v_cvt_pk_bf16_f32 v79, v94, v96
	s_waitcnt vmcnt(21)
	v_lshlrev_b32_e32 v94, 16, v76
	v_and_b32_e32 v76, 0xffff0000, v76
	v_lshlrev_b32_e32 v95, 16, v77
	v_and_b32_e32 v77, 0xffff0000, v77
	v_add_f32_e32 v96, v94, v76
	v_sub_f32_e32 v76, v94, v76
	v_add_f32_e32 v94, v95, v77
	v_sub_f32_e32 v77, v95, v77
	v_add_f32_e32 v95, v96, v94
	v_sub_f32_e32 v94, v96, v94
	v_add_f32_e32 v98, v76, v77
	v_sub_f32_e32 v76, v76, v77
	v_xor_b32_e32 v204, v82, v95
	v_xor_b32_e32 v205, v82, v94
	v_xor_b32_e32 v206, v82, v98
	v_xor_b32_e32 v207, v82, v76
	v_add_f32_dpp v77, v95, v204 quad_perm:[1,0,3,2] row_mask:0xf bank_mask:0xf bound_ctrl:1
	v_add_f32_dpp v94, v94, v205 quad_perm:[1,0,3,2] row_mask:0xf bank_mask:0xf bound_ctrl:1
	v_add_f32_dpp v95, v98, v206 quad_perm:[1,0,3,2] row_mask:0xf bank_mask:0xf bound_ctrl:1
	v_add_f32_dpp v76, v76, v207 quad_perm:[1,0,3,2] row_mask:0xf bank_mask:0xf bound_ctrl:1
	v_xor_b32_e32 v200, v83, v77
	v_xor_b32_e32 v201, v83, v95
	v_xor_b32_e32 v202, v83, v94
	v_xor_b32_e32 v203, v83, v76
	v_add_f32_dpp v204, v77, v200 quad_perm:[2,3,0,1] row_mask:0xf bank_mask:0xf bound_ctrl:1
	v_add_f32_dpp v205, v95, v201 quad_perm:[2,3,0,1] row_mask:0xf bank_mask:0xf bound_ctrl:1
	v_add_f32_dpp v206, v94, v202 quad_perm:[2,3,0,1] row_mask:0xf bank_mask:0xf bound_ctrl:1
	v_add_f32_dpp v207, v76, v203 quad_perm:[2,3,0,1] row_mask:0xf bank_mask:0xf bound_ctrl:1
	v_xor_b32_e32 v200, v84, v204
	v_xor_b32_e32 v201, v84, v205
	v_xor_b32_e32 v202, v84, v206
	v_xor_b32_e32 v203, v84, v207
	v_add_f32_dpp v77, v204, v200 row_shl:4 row_mask:0xf bank_mask:0x5
	v_add_f32_dpp v95, v205, v201 row_shl:4 row_mask:0xf bank_mask:0x5
	v_add_f32_dpp v94, v206, v202 row_shl:4 row_mask:0xf bank_mask:0x5
	v_add_f32_dpp v96, v207, v203 row_shl:4 row_mask:0xf bank_mask:0x5
	v_add_f32_dpp v77, v204, v200 row_shr:4 row_mask:0xf bank_mask:0xa
	v_add_f32_dpp v95, v205, v201 row_shr:4 row_mask:0xf bank_mask:0xa
	v_add_f32_dpp v94, v206, v202 row_shr:4 row_mask:0xf bank_mask:0xa
	v_add_f32_dpp v96, v207, v203 row_shr:4 row_mask:0xf bank_mask:0xa
	v_max_f32_e64 v76, |v77|, |v95|
	v_max_f32_e64 v98, |v94|, |v96|
	v_max3_f32 v97, v97, v76, v98
	v_cvt_pk_bf16_f32 v76, v77, v95
	v_cvt_pk_bf16_f32 v77, v94, v96
	s_waitcnt vmcnt(20)
	v_lshlrev_b32_e32 v94, 16, v74
	v_and_b32_e32 v74, 0xffff0000, v74
	v_lshlrev_b32_e32 v95, 16, v75
	v_and_b32_e32 v75, 0xffff0000, v75
	v_add_f32_e32 v96, v94, v74
	v_sub_f32_e32 v74, v94, v74
	v_add_f32_e32 v94, v95, v75
	v_sub_f32_e32 v75, v95, v75
	v_add_f32_e32 v95, v96, v94
	v_sub_f32_e32 v94, v96, v94
	v_add_f32_e32 v98, v74, v75
	v_sub_f32_e32 v74, v74, v75
	v_xor_b32_e32 v204, v82, v95
	v_xor_b32_e32 v205, v82, v94
	v_xor_b32_e32 v206, v82, v98
	v_xor_b32_e32 v207, v82, v74
	v_add_f32_dpp v75, v95, v204 quad_perm:[1,0,3,2] row_mask:0xf bank_mask:0xf bound_ctrl:1
	v_add_f32_dpp v94, v94, v205 quad_perm:[1,0,3,2] row_mask:0xf bank_mask:0xf bound_ctrl:1
	v_add_f32_dpp v95, v98, v206 quad_perm:[1,0,3,2] row_mask:0xf bank_mask:0xf bound_ctrl:1
	v_add_f32_dpp v74, v74, v207 quad_perm:[1,0,3,2] row_mask:0xf bank_mask:0xf bound_ctrl:1
	v_xor_b32_e32 v200, v83, v75
	v_xor_b32_e32 v201, v83, v95
	v_xor_b32_e32 v202, v83, v94
	v_xor_b32_e32 v203, v83, v74
	v_add_f32_dpp v204, v75, v200 quad_perm:[2,3,0,1] row_mask:0xf bank_mask:0xf bound_ctrl:1
	v_add_f32_dpp v205, v95, v201 quad_perm:[2,3,0,1] row_mask:0xf bank_mask:0xf bound_ctrl:1
	v_add_f32_dpp v206, v94, v202 quad_perm:[2,3,0,1] row_mask:0xf bank_mask:0xf bound_ctrl:1
	v_add_f32_dpp v207, v74, v203 quad_perm:[2,3,0,1] row_mask:0xf bank_mask:0xf bound_ctrl:1
	v_xor_b32_e32 v200, v84, v204
	v_xor_b32_e32 v201, v84, v205
	v_xor_b32_e32 v202, v84, v206
	v_xor_b32_e32 v203, v84, v207
	v_add_f32_dpp v75, v204, v200 row_shl:4 row_mask:0xf bank_mask:0x5
	v_add_f32_dpp v95, v205, v201 row_shl:4 row_mask:0xf bank_mask:0x5
	v_add_f32_dpp v94, v206, v202 row_shl:4 row_mask:0xf bank_mask:0x5
	v_add_f32_dpp v96, v207, v203 row_shl:4 row_mask:0xf bank_mask:0x5
	v_add_f32_dpp v75, v204, v200 row_shr:4 row_mask:0xf bank_mask:0xa
	v_add_f32_dpp v95, v205, v201 row_shr:4 row_mask:0xf bank_mask:0xa
	v_add_f32_dpp v94, v206, v202 row_shr:4 row_mask:0xf bank_mask:0xa
	v_add_f32_dpp v96, v207, v203 row_shr:4 row_mask:0xf bank_mask:0xa
	v_max_f32_e64 v74, |v75|, |v95|
	v_max_f32_e64 v98, |v94|, |v96|
	v_max3_f32 v97, v97, v74, v98
	v_cvt_pk_bf16_f32 v74, v75, v95
	v_cvt_pk_bf16_f32 v75, v94, v96
	s_waitcnt vmcnt(3)
	v_lshlrev_b32_e32 v94, 16, v72
	v_and_b32_e32 v72, 0xffff0000, v72
	v_lshlrev_b32_e32 v95, 16, v73
	v_and_b32_e32 v73, 0xffff0000, v73
	v_add_f32_e32 v96, v94, v72
	v_sub_f32_e32 v72, v94, v72
	v_add_f32_e32 v94, v95, v73
	v_sub_f32_e32 v73, v95, v73
	v_add_f32_e32 v95, v96, v94
	v_sub_f32_e32 v94, v96, v94
	v_add_f32_e32 v98, v72, v73
	v_sub_f32_e32 v72, v72, v73
	v_xor_b32_e32 v204, v82, v95
	v_xor_b32_e32 v205, v82, v94
	v_xor_b32_e32 v206, v82, v98
	v_xor_b32_e32 v207, v82, v72
	v_add_f32_dpp v73, v95, v204 quad_perm:[1,0,3,2] row_mask:0xf bank_mask:0xf bound_ctrl:1
	v_add_f32_dpp v94, v94, v205 quad_perm:[1,0,3,2] row_mask:0xf bank_mask:0xf bound_ctrl:1
	v_add_f32_dpp v95, v98, v206 quad_perm:[1,0,3,2] row_mask:0xf bank_mask:0xf bound_ctrl:1
	v_add_f32_dpp v72, v72, v207 quad_perm:[1,0,3,2] row_mask:0xf bank_mask:0xf bound_ctrl:1
	v_xor_b32_e32 v200, v83, v73
	v_xor_b32_e32 v201, v83, v95
	v_xor_b32_e32 v202, v83, v94
	v_xor_b32_e32 v203, v83, v72
	v_add_f32_dpp v204, v73, v200 quad_perm:[2,3,0,1] row_mask:0xf bank_mask:0xf bound_ctrl:1
	v_add_f32_dpp v205, v95, v201 quad_perm:[2,3,0,1] row_mask:0xf bank_mask:0xf bound_ctrl:1
	v_add_f32_dpp v206, v94, v202 quad_perm:[2,3,0,1] row_mask:0xf bank_mask:0xf bound_ctrl:1
	v_add_f32_dpp v207, v72, v203 quad_perm:[2,3,0,1] row_mask:0xf bank_mask:0xf bound_ctrl:1
	v_xor_b32_e32 v200, v84, v204
	v_xor_b32_e32 v201, v84, v205
	v_xor_b32_e32 v202, v84, v206
	v_xor_b32_e32 v203, v84, v207
	v_add_f32_dpp v73, v204, v200 row_shl:4 row_mask:0xf bank_mask:0x5
	v_add_f32_dpp v95, v205, v201 row_shl:4 row_mask:0xf bank_mask:0x5
	v_add_f32_dpp v94, v206, v202 row_shl:4 row_mask:0xf bank_mask:0x5
	v_add_f32_dpp v96, v207, v203 row_shl:4 row_mask:0xf bank_mask:0x5
	v_add_f32_dpp v73, v204, v200 row_shr:4 row_mask:0xf bank_mask:0xa
	v_add_f32_dpp v95, v205, v201 row_shr:4 row_mask:0xf bank_mask:0xa
	v_add_f32_dpp v94, v206, v202 row_shr:4 row_mask:0xf bank_mask:0xa
	v_add_f32_dpp v96, v207, v203 row_shr:4 row_mask:0xf bank_mask:0xa
	v_max_f32_e64 v72, |v73|, |v95|
	v_max_f32_e64 v98, |v94|, |v96|
	v_max3_f32 v97, v97, v72, v98
	v_cvt_pk_bf16_f32 v72, v73, v95
	v_cvt_pk_bf16_f32 v73, v94, v96
	v_lshlrev_b32_e32 v94, 16, v70
	v_and_b32_e32 v70, 0xffff0000, v70
	v_lshlrev_b32_e32 v95, 16, v71
	v_and_b32_e32 v71, 0xffff0000, v71
	v_add_f32_e32 v96, v94, v70
	v_sub_f32_e32 v70, v94, v70
	v_add_f32_e32 v94, v95, v71
	v_sub_f32_e32 v71, v95, v71
	v_add_f32_e32 v95, v96, v94
	v_sub_f32_e32 v94, v96, v94
	v_add_f32_e32 v98, v70, v71
	v_sub_f32_e32 v70, v70, v71
	v_xor_b32_e32 v204, v82, v95
	v_xor_b32_e32 v205, v82, v94
	v_xor_b32_e32 v206, v82, v98
	v_xor_b32_e32 v207, v82, v70
	v_add_f32_dpp v71, v95, v204 quad_perm:[1,0,3,2] row_mask:0xf bank_mask:0xf bound_ctrl:1
	v_add_f32_dpp v94, v94, v205 quad_perm:[1,0,3,2] row_mask:0xf bank_mask:0xf bound_ctrl:1
	v_add_f32_dpp v95, v98, v206 quad_perm:[1,0,3,2] row_mask:0xf bank_mask:0xf bound_ctrl:1
	v_add_f32_dpp v70, v70, v207 quad_perm:[1,0,3,2] row_mask:0xf bank_mask:0xf bound_ctrl:1
	v_xor_b32_e32 v200, v83, v71
	v_xor_b32_e32 v201, v83, v95
	v_xor_b32_e32 v202, v83, v94
	v_xor_b32_e32 v203, v83, v70
	v_add_f32_dpp v204, v71, v200 quad_perm:[2,3,0,1] row_mask:0xf bank_mask:0xf bound_ctrl:1
	v_add_f32_dpp v205, v95, v201 quad_perm:[2,3,0,1] row_mask:0xf bank_mask:0xf bound_ctrl:1
	v_add_f32_dpp v206, v94, v202 quad_perm:[2,3,0,1] row_mask:0xf bank_mask:0xf bound_ctrl:1
	v_add_f32_dpp v207, v70, v203 quad_perm:[2,3,0,1] row_mask:0xf bank_mask:0xf bound_ctrl:1
	v_xor_b32_e32 v200, v84, v204
	v_xor_b32_e32 v201, v84, v205
	v_xor_b32_e32 v202, v84, v206
	v_xor_b32_e32 v203, v84, v207
	v_add_f32_dpp v71, v204, v200 row_shl:4 row_mask:0xf bank_mask:0x5
	v_add_f32_dpp v95, v205, v201 row_shl:4 row_mask:0xf bank_mask:0x5
	v_add_f32_dpp v94, v206, v202 row_shl:4 row_mask:0xf bank_mask:0x5
	v_add_f32_dpp v96, v207, v203 row_shl:4 row_mask:0xf bank_mask:0x5
	v_add_f32_dpp v71, v204, v200 row_shr:4 row_mask:0xf bank_mask:0xa
	v_add_f32_dpp v95, v205, v201 row_shr:4 row_mask:0xf bank_mask:0xa
	v_add_f32_dpp v94, v206, v202 row_shr:4 row_mask:0xf bank_mask:0xa
	v_add_f32_dpp v96, v207, v203 row_shr:4 row_mask:0xf bank_mask:0xa
	v_max_f32_e64 v70, |v71|, |v95|
	v_max_f32_e64 v98, |v94|, |v96|
	v_max3_f32 v97, v97, v70, v98
	v_cvt_pk_bf16_f32 v70, v71, v95
	v_cvt_pk_bf16_f32 v71, v94, v96
	v_lshlrev_b32_e32 v94, 16, v68
	v_and_b32_e32 v68, 0xffff0000, v68
	v_lshlrev_b32_e32 v95, 16, v69
	v_and_b32_e32 v69, 0xffff0000, v69
	v_add_f32_e32 v96, v94, v68
	v_sub_f32_e32 v68, v94, v68
	v_add_f32_e32 v94, v95, v69
	v_sub_f32_e32 v69, v95, v69
	v_add_f32_e32 v95, v96, v94
	v_sub_f32_e32 v94, v96, v94
	v_add_f32_e32 v98, v68, v69
	v_sub_f32_e32 v68, v68, v69
	v_xor_b32_e32 v204, v82, v95
	v_xor_b32_e32 v205, v82, v94
	v_xor_b32_e32 v206, v82, v98
	v_xor_b32_e32 v207, v82, v68
	v_add_f32_dpp v69, v95, v204 quad_perm:[1,0,3,2] row_mask:0xf bank_mask:0xf bound_ctrl:1
	v_add_f32_dpp v94, v94, v205 quad_perm:[1,0,3,2] row_mask:0xf bank_mask:0xf bound_ctrl:1
	v_add_f32_dpp v95, v98, v206 quad_perm:[1,0,3,2] row_mask:0xf bank_mask:0xf bound_ctrl:1
	v_add_f32_dpp v68, v68, v207 quad_perm:[1,0,3,2] row_mask:0xf bank_mask:0xf bound_ctrl:1
	v_xor_b32_e32 v200, v83, v69
	v_xor_b32_e32 v201, v83, v95
	v_xor_b32_e32 v202, v83, v94
	v_xor_b32_e32 v203, v83, v68
	v_add_f32_dpp v204, v69, v200 quad_perm:[2,3,0,1] row_mask:0xf bank_mask:0xf bound_ctrl:1
	v_add_f32_dpp v205, v95, v201 quad_perm:[2,3,0,1] row_mask:0xf bank_mask:0xf bound_ctrl:1
	v_add_f32_dpp v206, v94, v202 quad_perm:[2,3,0,1] row_mask:0xf bank_mask:0xf bound_ctrl:1
	v_add_f32_dpp v207, v68, v203 quad_perm:[2,3,0,1] row_mask:0xf bank_mask:0xf bound_ctrl:1
	v_xor_b32_e32 v200, v84, v204
	v_xor_b32_e32 v201, v84, v205
	v_xor_b32_e32 v202, v84, v206
	v_xor_b32_e32 v203, v84, v207
	v_add_f32_dpp v69, v204, v200 row_shl:4 row_mask:0xf bank_mask:0x5
	v_add_f32_dpp v95, v205, v201 row_shl:4 row_mask:0xf bank_mask:0x5
	v_add_f32_dpp v94, v206, v202 row_shl:4 row_mask:0xf bank_mask:0x5
	v_add_f32_dpp v96, v207, v203 row_shl:4 row_mask:0xf bank_mask:0x5
	v_add_f32_dpp v69, v204, v200 row_shr:4 row_mask:0xf bank_mask:0xa
	v_add_f32_dpp v95, v205, v201 row_shr:4 row_mask:0xf bank_mask:0xa
	v_add_f32_dpp v94, v206, v202 row_shr:4 row_mask:0xf bank_mask:0xa
	v_add_f32_dpp v96, v207, v203 row_shr:4 row_mask:0xf bank_mask:0xa
	v_max_f32_e64 v68, |v69|, |v95|
	v_max_f32_e64 v98, |v94|, |v96|
	v_max3_f32 v97, v97, v68, v98
	v_cvt_pk_bf16_f32 v68, v69, v95
	v_cvt_pk_bf16_f32 v69, v94, v96
	v_lshlrev_b32_e32 v94, 16, v66
	v_and_b32_e32 v66, 0xffff0000, v66
	v_lshlrev_b32_e32 v95, 16, v67
	v_and_b32_e32 v67, 0xffff0000, v67
	v_add_f32_e32 v96, v94, v66
	v_sub_f32_e32 v66, v94, v66
	v_add_f32_e32 v94, v95, v67
	v_sub_f32_e32 v67, v95, v67
	v_add_f32_e32 v95, v96, v94
	v_sub_f32_e32 v94, v96, v94
	v_add_f32_e32 v98, v66, v67
	v_sub_f32_e32 v66, v66, v67
	v_xor_b32_e32 v204, v82, v95
	v_xor_b32_e32 v205, v82, v94
	v_xor_b32_e32 v206, v82, v98
	v_xor_b32_e32 v207, v82, v66
	v_add_f32_dpp v67, v95, v204 quad_perm:[1,0,3,2] row_mask:0xf bank_mask:0xf bound_ctrl:1
	v_add_f32_dpp v94, v94, v205 quad_perm:[1,0,3,2] row_mask:0xf bank_mask:0xf bound_ctrl:1
	v_add_f32_dpp v95, v98, v206 quad_perm:[1,0,3,2] row_mask:0xf bank_mask:0xf bound_ctrl:1
	v_add_f32_dpp v66, v66, v207 quad_perm:[1,0,3,2] row_mask:0xf bank_mask:0xf bound_ctrl:1
	v_xor_b32_e32 v200, v83, v67
	v_xor_b32_e32 v201, v83, v95
	v_xor_b32_e32 v202, v83, v94
	v_xor_b32_e32 v203, v83, v66
	v_add_f32_dpp v204, v67, v200 quad_perm:[2,3,0,1] row_mask:0xf bank_mask:0xf bound_ctrl:1
	v_add_f32_dpp v205, v95, v201 quad_perm:[2,3,0,1] row_mask:0xf bank_mask:0xf bound_ctrl:1
	v_add_f32_dpp v206, v94, v202 quad_perm:[2,3,0,1] row_mask:0xf bank_mask:0xf bound_ctrl:1
	v_add_f32_dpp v207, v66, v203 quad_perm:[2,3,0,1] row_mask:0xf bank_mask:0xf bound_ctrl:1
	v_xor_b32_e32 v200, v84, v204
	v_xor_b32_e32 v201, v84, v205
	v_xor_b32_e32 v202, v84, v206
	v_xor_b32_e32 v203, v84, v207
	v_add_f32_dpp v67, v204, v200 row_shl:4 row_mask:0xf bank_mask:0x5
	v_add_f32_dpp v95, v205, v201 row_shl:4 row_mask:0xf bank_mask:0x5
	v_add_f32_dpp v94, v206, v202 row_shl:4 row_mask:0xf bank_mask:0x5
	v_add_f32_dpp v96, v207, v203 row_shl:4 row_mask:0xf bank_mask:0x5
	v_add_f32_dpp v67, v204, v200 row_shr:4 row_mask:0xf bank_mask:0xa
	v_add_f32_dpp v95, v205, v201 row_shr:4 row_mask:0xf bank_mask:0xa
	v_add_f32_dpp v94, v206, v202 row_shr:4 row_mask:0xf bank_mask:0xa
	v_add_f32_dpp v96, v207, v203 row_shr:4 row_mask:0xf bank_mask:0xa
	v_max_f32_e64 v66, |v67|, |v95|
	v_max_f32_e64 v98, |v94|, |v96|
	v_max3_f32 v97, v97, v66, v98
	v_cvt_pk_bf16_f32 v66, v67, v95
	v_cvt_pk_bf16_f32 v67, v94, v96
	v_lshlrev_b32_e32 v94, 16, v64
	v_and_b32_e32 v64, 0xffff0000, v64
	v_lshlrev_b32_e32 v95, 16, v65
	v_and_b32_e32 v65, 0xffff0000, v65
	v_add_f32_e32 v96, v94, v64
	v_sub_f32_e32 v64, v94, v64
	v_add_f32_e32 v94, v95, v65
	v_sub_f32_e32 v65, v95, v65
	v_add_f32_e32 v95, v96, v94
	v_sub_f32_e32 v94, v96, v94
	v_add_f32_e32 v98, v64, v65
	v_sub_f32_e32 v64, v64, v65
	v_xor_b32_e32 v204, v82, v95
	v_xor_b32_e32 v205, v82, v94
	v_xor_b32_e32 v206, v82, v98
	v_xor_b32_e32 v207, v82, v64
	v_add_f32_dpp v65, v95, v204 quad_perm:[1,0,3,2] row_mask:0xf bank_mask:0xf bound_ctrl:1
	v_add_f32_dpp v94, v94, v205 quad_perm:[1,0,3,2] row_mask:0xf bank_mask:0xf bound_ctrl:1
	v_add_f32_dpp v95, v98, v206 quad_perm:[1,0,3,2] row_mask:0xf bank_mask:0xf bound_ctrl:1
	v_add_f32_dpp v64, v64, v207 quad_perm:[1,0,3,2] row_mask:0xf bank_mask:0xf bound_ctrl:1
	v_xor_b32_e32 v200, v83, v65
	v_xor_b32_e32 v201, v83, v95
	v_xor_b32_e32 v202, v83, v94
	v_xor_b32_e32 v203, v83, v64
	v_add_f32_dpp v204, v65, v200 quad_perm:[2,3,0,1] row_mask:0xf bank_mask:0xf bound_ctrl:1
	v_add_f32_dpp v205, v95, v201 quad_perm:[2,3,0,1] row_mask:0xf bank_mask:0xf bound_ctrl:1
	v_add_f32_dpp v206, v94, v202 quad_perm:[2,3,0,1] row_mask:0xf bank_mask:0xf bound_ctrl:1
	v_add_f32_dpp v207, v64, v203 quad_perm:[2,3,0,1] row_mask:0xf bank_mask:0xf bound_ctrl:1
	v_xor_b32_e32 v200, v84, v204
	v_xor_b32_e32 v201, v84, v205
	v_xor_b32_e32 v202, v84, v206
	v_xor_b32_e32 v203, v84, v207
	v_add_f32_dpp v65, v204, v200 row_shl:4 row_mask:0xf bank_mask:0x5
	v_add_f32_dpp v95, v205, v201 row_shl:4 row_mask:0xf bank_mask:0x5
	v_add_f32_dpp v94, v206, v202 row_shl:4 row_mask:0xf bank_mask:0x5
	v_add_f32_dpp v96, v207, v203 row_shl:4 row_mask:0xf bank_mask:0x5
	v_add_f32_dpp v65, v204, v200 row_shr:4 row_mask:0xf bank_mask:0xa
	v_add_f32_dpp v95, v205, v201 row_shr:4 row_mask:0xf bank_mask:0xa
	v_add_f32_dpp v94, v206, v202 row_shr:4 row_mask:0xf bank_mask:0xa
	v_add_f32_dpp v96, v207, v203 row_shr:4 row_mask:0xf bank_mask:0xa
	v_max_f32_e64 v64, |v65|, |v95|
	v_max_f32_e64 v98, |v94|, |v96|
	v_max3_f32 v97, v97, v64, v98
	v_cvt_pk_bf16_f32 v64, v65, v95
	v_cvt_pk_bf16_f32 v65, v94, v96
	v_lshlrev_b32_e32 v94, 16, v62
	v_and_b32_e32 v62, 0xffff0000, v62
	v_lshlrev_b32_e32 v95, 16, v63
	v_and_b32_e32 v63, 0xffff0000, v63
	v_add_f32_e32 v96, v94, v62
	v_sub_f32_e32 v62, v94, v62
	v_add_f32_e32 v94, v95, v63
	v_sub_f32_e32 v63, v95, v63
	v_add_f32_e32 v95, v96, v94
	v_sub_f32_e32 v94, v96, v94
	v_add_f32_e32 v98, v62, v63
	v_sub_f32_e32 v62, v62, v63
	v_xor_b32_e32 v204, v82, v95
	v_xor_b32_e32 v205, v82, v94
	v_xor_b32_e32 v206, v82, v98
	v_xor_b32_e32 v207, v82, v62
	v_add_f32_dpp v63, v95, v204 quad_perm:[1,0,3,2] row_mask:0xf bank_mask:0xf bound_ctrl:1
	v_add_f32_dpp v94, v94, v205 quad_perm:[1,0,3,2] row_mask:0xf bank_mask:0xf bound_ctrl:1
	v_add_f32_dpp v95, v98, v206 quad_perm:[1,0,3,2] row_mask:0xf bank_mask:0xf bound_ctrl:1
	v_add_f32_dpp v62, v62, v207 quad_perm:[1,0,3,2] row_mask:0xf bank_mask:0xf bound_ctrl:1
	v_xor_b32_e32 v200, v83, v63
	v_xor_b32_e32 v201, v83, v95
	v_xor_b32_e32 v202, v83, v94
	v_xor_b32_e32 v203, v83, v62
	v_add_f32_dpp v204, v63, v200 quad_perm:[2,3,0,1] row_mask:0xf bank_mask:0xf bound_ctrl:1
	v_add_f32_dpp v205, v95, v201 quad_perm:[2,3,0,1] row_mask:0xf bank_mask:0xf bound_ctrl:1
	v_add_f32_dpp v206, v94, v202 quad_perm:[2,3,0,1] row_mask:0xf bank_mask:0xf bound_ctrl:1
	v_add_f32_dpp v207, v62, v203 quad_perm:[2,3,0,1] row_mask:0xf bank_mask:0xf bound_ctrl:1
	v_xor_b32_e32 v200, v84, v204
	v_xor_b32_e32 v201, v84, v205
	v_xor_b32_e32 v202, v84, v206
	v_xor_b32_e32 v203, v84, v207
	v_add_f32_dpp v63, v204, v200 row_shl:4 row_mask:0xf bank_mask:0x5
	v_add_f32_dpp v95, v205, v201 row_shl:4 row_mask:0xf bank_mask:0x5
	v_add_f32_dpp v94, v206, v202 row_shl:4 row_mask:0xf bank_mask:0x5
	v_add_f32_dpp v96, v207, v203 row_shl:4 row_mask:0xf bank_mask:0x5
	v_add_f32_dpp v63, v204, v200 row_shr:4 row_mask:0xf bank_mask:0xa
	v_add_f32_dpp v95, v205, v201 row_shr:4 row_mask:0xf bank_mask:0xa
	v_add_f32_dpp v94, v206, v202 row_shr:4 row_mask:0xf bank_mask:0xa
	v_add_f32_dpp v96, v207, v203 row_shr:4 row_mask:0xf bank_mask:0xa
	v_max_f32_e64 v62, |v63|, |v95|
	v_max_f32_e64 v98, |v94|, |v96|
	v_max3_f32 v97, v97, v62, v98
	v_cvt_pk_bf16_f32 v62, v63, v95
	v_cvt_pk_bf16_f32 v63, v94, v96
	v_lshlrev_b32_e32 v94, 16, v60
	v_and_b32_e32 v60, 0xffff0000, v60
	v_lshlrev_b32_e32 v95, 16, v61
	v_and_b32_e32 v61, 0xffff0000, v61
	v_add_f32_e32 v96, v94, v60
	v_sub_f32_e32 v60, v94, v60
	v_add_f32_e32 v94, v95, v61
	v_sub_f32_e32 v61, v95, v61
	v_add_f32_e32 v95, v96, v94
	v_sub_f32_e32 v94, v96, v94
	v_add_f32_e32 v98, v60, v61
	v_sub_f32_e32 v60, v60, v61
	v_xor_b32_e32 v204, v82, v95
	v_xor_b32_e32 v205, v82, v94
	v_xor_b32_e32 v206, v82, v98
	v_xor_b32_e32 v207, v82, v60
	v_add_f32_dpp v61, v95, v204 quad_perm:[1,0,3,2] row_mask:0xf bank_mask:0xf bound_ctrl:1
	v_add_f32_dpp v94, v94, v205 quad_perm:[1,0,3,2] row_mask:0xf bank_mask:0xf bound_ctrl:1
	v_add_f32_dpp v95, v98, v206 quad_perm:[1,0,3,2] row_mask:0xf bank_mask:0xf bound_ctrl:1
	v_add_f32_dpp v60, v60, v207 quad_perm:[1,0,3,2] row_mask:0xf bank_mask:0xf bound_ctrl:1
	v_xor_b32_e32 v200, v83, v61
	v_xor_b32_e32 v201, v83, v95
	v_xor_b32_e32 v202, v83, v94
	v_xor_b32_e32 v203, v83, v60
	v_add_f32_dpp v204, v61, v200 quad_perm:[2,3,0,1] row_mask:0xf bank_mask:0xf bound_ctrl:1
	v_add_f32_dpp v205, v95, v201 quad_perm:[2,3,0,1] row_mask:0xf bank_mask:0xf bound_ctrl:1
	v_add_f32_dpp v206, v94, v202 quad_perm:[2,3,0,1] row_mask:0xf bank_mask:0xf bound_ctrl:1
	v_add_f32_dpp v207, v60, v203 quad_perm:[2,3,0,1] row_mask:0xf bank_mask:0xf bound_ctrl:1
	v_xor_b32_e32 v200, v84, v204
	v_xor_b32_e32 v201, v84, v205
	v_xor_b32_e32 v202, v84, v206
	v_xor_b32_e32 v203, v84, v207
	v_add_f32_dpp v61, v204, v200 row_shl:4 row_mask:0xf bank_mask:0x5
	v_add_f32_dpp v95, v205, v201 row_shl:4 row_mask:0xf bank_mask:0x5
	v_add_f32_dpp v94, v206, v202 row_shl:4 row_mask:0xf bank_mask:0x5
	v_add_f32_dpp v96, v207, v203 row_shl:4 row_mask:0xf bank_mask:0x5
	v_add_f32_dpp v61, v204, v200 row_shr:4 row_mask:0xf bank_mask:0xa
	v_add_f32_dpp v95, v205, v201 row_shr:4 row_mask:0xf bank_mask:0xa
	v_add_f32_dpp v94, v206, v202 row_shr:4 row_mask:0xf bank_mask:0xa
	v_add_f32_dpp v96, v207, v203 row_shr:4 row_mask:0xf bank_mask:0xa
	v_max_f32_e64 v60, |v61|, |v95|
	v_max_f32_e64 v98, |v94|, |v96|
	v_max3_f32 v97, v97, v60, v98
	v_cvt_pk_bf16_f32 v60, v61, v95
	v_cvt_pk_bf16_f32 v61, v94, v96
	v_lshlrev_b32_e32 v94, 16, v58
	v_and_b32_e32 v58, 0xffff0000, v58
	v_lshlrev_b32_e32 v95, 16, v59
	v_and_b32_e32 v59, 0xffff0000, v59
	v_add_f32_e32 v96, v94, v58
	v_sub_f32_e32 v58, v94, v58
	v_add_f32_e32 v94, v95, v59
	v_sub_f32_e32 v59, v95, v59
	v_add_f32_e32 v95, v96, v94
	v_sub_f32_e32 v94, v96, v94
	v_add_f32_e32 v98, v58, v59
	v_sub_f32_e32 v58, v58, v59
	v_xor_b32_e32 v204, v82, v95
	v_xor_b32_e32 v205, v82, v94
	v_xor_b32_e32 v206, v82, v98
	v_xor_b32_e32 v207, v82, v58
	v_add_f32_dpp v59, v95, v204 quad_perm:[1,0,3,2] row_mask:0xf bank_mask:0xf bound_ctrl:1
	v_add_f32_dpp v94, v94, v205 quad_perm:[1,0,3,2] row_mask:0xf bank_mask:0xf bound_ctrl:1
	v_add_f32_dpp v95, v98, v206 quad_perm:[1,0,3,2] row_mask:0xf bank_mask:0xf bound_ctrl:1
	v_add_f32_dpp v58, v58, v207 quad_perm:[1,0,3,2] row_mask:0xf bank_mask:0xf bound_ctrl:1
	v_xor_b32_e32 v200, v83, v59
	v_xor_b32_e32 v201, v83, v95
	v_xor_b32_e32 v202, v83, v94
	v_xor_b32_e32 v203, v83, v58
	v_add_f32_dpp v204, v59, v200 quad_perm:[2,3,0,1] row_mask:0xf bank_mask:0xf bound_ctrl:1
	v_add_f32_dpp v205, v95, v201 quad_perm:[2,3,0,1] row_mask:0xf bank_mask:0xf bound_ctrl:1
	v_add_f32_dpp v206, v94, v202 quad_perm:[2,3,0,1] row_mask:0xf bank_mask:0xf bound_ctrl:1
	v_add_f32_dpp v207, v58, v203 quad_perm:[2,3,0,1] row_mask:0xf bank_mask:0xf bound_ctrl:1
	v_xor_b32_e32 v200, v84, v204
	v_xor_b32_e32 v201, v84, v205
	v_xor_b32_e32 v202, v84, v206
	v_xor_b32_e32 v203, v84, v207
	v_add_f32_dpp v59, v204, v200 row_shl:4 row_mask:0xf bank_mask:0x5
	v_add_f32_dpp v95, v205, v201 row_shl:4 row_mask:0xf bank_mask:0x5
	v_add_f32_dpp v94, v206, v202 row_shl:4 row_mask:0xf bank_mask:0x5
	v_add_f32_dpp v96, v207, v203 row_shl:4 row_mask:0xf bank_mask:0x5
	v_add_f32_dpp v59, v204, v200 row_shr:4 row_mask:0xf bank_mask:0xa
	v_add_f32_dpp v95, v205, v201 row_shr:4 row_mask:0xf bank_mask:0xa
	v_add_f32_dpp v94, v206, v202 row_shr:4 row_mask:0xf bank_mask:0xa
	v_add_f32_dpp v96, v207, v203 row_shr:4 row_mask:0xf bank_mask:0xa
	v_max_f32_e64 v58, |v59|, |v95|
	v_max_f32_e64 v98, |v94|, |v96|
	v_max3_f32 v97, v97, v58, v98
	v_cvt_pk_bf16_f32 v58, v59, v95
	v_cvt_pk_bf16_f32 v59, v94, v96
	s_waitcnt vmcnt(2)
	v_lshlrev_b32_e32 v94, 16, v56
	v_and_b32_e32 v56, 0xffff0000, v56
	v_lshlrev_b32_e32 v95, 16, v57
	v_and_b32_e32 v57, 0xffff0000, v57
	v_add_f32_e32 v96, v94, v56
	v_sub_f32_e32 v56, v94, v56
	v_add_f32_e32 v94, v95, v57
	v_sub_f32_e32 v57, v95, v57
	v_add_f32_e32 v95, v96, v94
	v_sub_f32_e32 v94, v96, v94
	v_add_f32_e32 v98, v56, v57
	v_sub_f32_e32 v56, v56, v57
	v_xor_b32_e32 v204, v82, v95
	v_xor_b32_e32 v205, v82, v94
	v_xor_b32_e32 v206, v82, v98
	v_xor_b32_e32 v207, v82, v56
	v_add_f32_dpp v57, v95, v204 quad_perm:[1,0,3,2] row_mask:0xf bank_mask:0xf bound_ctrl:1
	v_add_f32_dpp v94, v94, v205 quad_perm:[1,0,3,2] row_mask:0xf bank_mask:0xf bound_ctrl:1
	v_add_f32_dpp v95, v98, v206 quad_perm:[1,0,3,2] row_mask:0xf bank_mask:0xf bound_ctrl:1
	v_add_f32_dpp v56, v56, v207 quad_perm:[1,0,3,2] row_mask:0xf bank_mask:0xf bound_ctrl:1
	v_xor_b32_e32 v200, v83, v57
	v_xor_b32_e32 v201, v83, v95
	v_xor_b32_e32 v202, v83, v94
	v_xor_b32_e32 v203, v83, v56
	v_add_f32_dpp v204, v57, v200 quad_perm:[2,3,0,1] row_mask:0xf bank_mask:0xf bound_ctrl:1
	v_add_f32_dpp v205, v95, v201 quad_perm:[2,3,0,1] row_mask:0xf bank_mask:0xf bound_ctrl:1
	v_add_f32_dpp v206, v94, v202 quad_perm:[2,3,0,1] row_mask:0xf bank_mask:0xf bound_ctrl:1
	v_add_f32_dpp v207, v56, v203 quad_perm:[2,3,0,1] row_mask:0xf bank_mask:0xf bound_ctrl:1
	v_xor_b32_e32 v200, v84, v204
	v_xor_b32_e32 v201, v84, v205
	v_xor_b32_e32 v202, v84, v206
	v_xor_b32_e32 v203, v84, v207
	v_add_f32_dpp v57, v204, v200 row_shl:4 row_mask:0xf bank_mask:0x5
	v_add_f32_dpp v95, v205, v201 row_shl:4 row_mask:0xf bank_mask:0x5
	v_add_f32_dpp v94, v206, v202 row_shl:4 row_mask:0xf bank_mask:0x5
	v_add_f32_dpp v96, v207, v203 row_shl:4 row_mask:0xf bank_mask:0x5
	v_add_f32_dpp v57, v204, v200 row_shr:4 row_mask:0xf bank_mask:0xa
	v_add_f32_dpp v95, v205, v201 row_shr:4 row_mask:0xf bank_mask:0xa
	v_add_f32_dpp v94, v206, v202 row_shr:4 row_mask:0xf bank_mask:0xa
	v_add_f32_dpp v96, v207, v203 row_shr:4 row_mask:0xf bank_mask:0xa
	v_max_f32_e64 v56, |v57|, |v95|
	v_max_f32_e64 v98, |v94|, |v96|
	v_max3_f32 v97, v97, v56, v98
	v_cvt_pk_bf16_f32 v56, v57, v95
	v_cvt_pk_bf16_f32 v57, v94, v96
	s_waitcnt vmcnt(1)
	v_lshlrev_b32_e32 v94, 16, v54
	v_and_b32_e32 v54, 0xffff0000, v54
	v_lshlrev_b32_e32 v95, 16, v55
	v_and_b32_e32 v55, 0xffff0000, v55
	v_add_f32_e32 v96, v94, v54
	v_sub_f32_e32 v54, v94, v54
	v_add_f32_e32 v94, v95, v55
	v_sub_f32_e32 v55, v95, v55
	v_add_f32_e32 v95, v96, v94
	v_sub_f32_e32 v94, v96, v94
	v_add_f32_e32 v98, v54, v55
	v_sub_f32_e32 v54, v54, v55
	v_xor_b32_e32 v204, v82, v95
	v_xor_b32_e32 v205, v82, v94
	v_xor_b32_e32 v206, v82, v98
	v_xor_b32_e32 v207, v82, v54
	v_add_f32_dpp v55, v95, v204 quad_perm:[1,0,3,2] row_mask:0xf bank_mask:0xf bound_ctrl:1
	v_add_f32_dpp v94, v94, v205 quad_perm:[1,0,3,2] row_mask:0xf bank_mask:0xf bound_ctrl:1
	v_add_f32_dpp v95, v98, v206 quad_perm:[1,0,3,2] row_mask:0xf bank_mask:0xf bound_ctrl:1
	v_add_f32_dpp v54, v54, v207 quad_perm:[1,0,3,2] row_mask:0xf bank_mask:0xf bound_ctrl:1
	v_xor_b32_e32 v200, v83, v55
	v_xor_b32_e32 v201, v83, v95
	v_xor_b32_e32 v202, v83, v94
	v_xor_b32_e32 v203, v83, v54
	v_add_f32_dpp v204, v55, v200 quad_perm:[2,3,0,1] row_mask:0xf bank_mask:0xf bound_ctrl:1
	v_add_f32_dpp v205, v95, v201 quad_perm:[2,3,0,1] row_mask:0xf bank_mask:0xf bound_ctrl:1
	v_add_f32_dpp v206, v94, v202 quad_perm:[2,3,0,1] row_mask:0xf bank_mask:0xf bound_ctrl:1
	v_add_f32_dpp v207, v54, v203 quad_perm:[2,3,0,1] row_mask:0xf bank_mask:0xf bound_ctrl:1
	v_xor_b32_e32 v200, v84, v204
	v_xor_b32_e32 v201, v84, v205
	v_xor_b32_e32 v202, v84, v206
	v_xor_b32_e32 v203, v84, v207
	v_add_f32_dpp v55, v204, v200 row_shl:4 row_mask:0xf bank_mask:0x5
	v_add_f32_dpp v95, v205, v201 row_shl:4 row_mask:0xf bank_mask:0x5
	v_add_f32_dpp v94, v206, v202 row_shl:4 row_mask:0xf bank_mask:0x5
	v_add_f32_dpp v96, v207, v203 row_shl:4 row_mask:0xf bank_mask:0x5
	v_add_f32_dpp v55, v204, v200 row_shr:4 row_mask:0xf bank_mask:0xa
	v_add_f32_dpp v95, v205, v201 row_shr:4 row_mask:0xf bank_mask:0xa
	v_add_f32_dpp v94, v206, v202 row_shr:4 row_mask:0xf bank_mask:0xa
	v_add_f32_dpp v96, v207, v203 row_shr:4 row_mask:0xf bank_mask:0xa
	v_max_f32_e64 v54, |v55|, |v95|
	v_max_f32_e64 v98, |v94|, |v96|
	v_max3_f32 v97, v97, v54, v98
	v_cvt_pk_bf16_f32 v54, v55, v95
	v_cvt_pk_bf16_f32 v55, v94, v96
	v_lshlrev_b32_e32 v94, 16, v52
	v_and_b32_e32 v52, 0xffff0000, v52
	v_lshlrev_b32_e32 v95, 16, v53
	v_and_b32_e32 v53, 0xffff0000, v53
	v_add_f32_e32 v96, v94, v52
	v_sub_f32_e32 v52, v94, v52
	v_add_f32_e32 v94, v95, v53
	v_sub_f32_e32 v53, v95, v53
	v_add_f32_e32 v95, v96, v94
	v_sub_f32_e32 v94, v96, v94
	v_add_f32_e32 v98, v52, v53
	v_sub_f32_e32 v52, v52, v53
	v_xor_b32_e32 v204, v82, v95
	v_xor_b32_e32 v205, v82, v94
	v_xor_b32_e32 v206, v82, v98
	v_xor_b32_e32 v207, v82, v52
	v_add_f32_dpp v53, v95, v204 quad_perm:[1,0,3,2] row_mask:0xf bank_mask:0xf bound_ctrl:1
	v_add_f32_dpp v94, v94, v205 quad_perm:[1,0,3,2] row_mask:0xf bank_mask:0xf bound_ctrl:1
	v_add_f32_dpp v95, v98, v206 quad_perm:[1,0,3,2] row_mask:0xf bank_mask:0xf bound_ctrl:1
	v_add_f32_dpp v52, v52, v207 quad_perm:[1,0,3,2] row_mask:0xf bank_mask:0xf bound_ctrl:1
	v_xor_b32_e32 v200, v83, v53
	v_xor_b32_e32 v201, v83, v95
	v_xor_b32_e32 v202, v83, v94
	v_xor_b32_e32 v203, v83, v52
	v_add_f32_dpp v204, v53, v200 quad_perm:[2,3,0,1] row_mask:0xf bank_mask:0xf bound_ctrl:1
	v_add_f32_dpp v205, v95, v201 quad_perm:[2,3,0,1] row_mask:0xf bank_mask:0xf bound_ctrl:1
	v_add_f32_dpp v206, v94, v202 quad_perm:[2,3,0,1] row_mask:0xf bank_mask:0xf bound_ctrl:1
	v_add_f32_dpp v207, v52, v203 quad_perm:[2,3,0,1] row_mask:0xf bank_mask:0xf bound_ctrl:1
	v_xor_b32_e32 v200, v84, v204
	v_xor_b32_e32 v201, v84, v205
	v_xor_b32_e32 v202, v84, v206
	v_xor_b32_e32 v203, v84, v207
	v_add_f32_dpp v53, v204, v200 row_shl:4 row_mask:0xf bank_mask:0x5
	v_add_f32_dpp v95, v205, v201 row_shl:4 row_mask:0xf bank_mask:0x5
	v_add_f32_dpp v94, v206, v202 row_shl:4 row_mask:0xf bank_mask:0x5
	v_add_f32_dpp v96, v207, v203 row_shl:4 row_mask:0xf bank_mask:0x5
	v_add_f32_dpp v53, v204, v200 row_shr:4 row_mask:0xf bank_mask:0xa
	v_add_f32_dpp v95, v205, v201 row_shr:4 row_mask:0xf bank_mask:0xa
	v_add_f32_dpp v94, v206, v202 row_shr:4 row_mask:0xf bank_mask:0xa
	v_add_f32_dpp v96, v207, v203 row_shr:4 row_mask:0xf bank_mask:0xa
	v_max_f32_e64 v52, |v53|, |v95|
	v_max_f32_e64 v98, |v94|, |v96|
	v_max3_f32 v97, v97, v52, v98
	v_cvt_pk_bf16_f32 v52, v53, v95
	v_cvt_pk_bf16_f32 v53, v94, v96
	v_lshlrev_b32_e32 v94, 16, v50
	v_and_b32_e32 v50, 0xffff0000, v50
	v_lshlrev_b32_e32 v95, 16, v51
	v_and_b32_e32 v51, 0xffff0000, v51
	v_add_f32_e32 v96, v94, v50
	v_sub_f32_e32 v50, v94, v50
	v_add_f32_e32 v94, v95, v51
	v_sub_f32_e32 v51, v95, v51
	v_add_f32_e32 v95, v96, v94
	v_sub_f32_e32 v94, v96, v94
	v_add_f32_e32 v98, v50, v51
	v_sub_f32_e32 v50, v50, v51
	v_xor_b32_e32 v204, v82, v95
	v_xor_b32_e32 v205, v82, v94
	v_xor_b32_e32 v206, v82, v98
	v_xor_b32_e32 v207, v82, v50
	v_add_f32_dpp v51, v95, v204 quad_perm:[1,0,3,2] row_mask:0xf bank_mask:0xf bound_ctrl:1
	v_add_f32_dpp v94, v94, v205 quad_perm:[1,0,3,2] row_mask:0xf bank_mask:0xf bound_ctrl:1
	v_add_f32_dpp v95, v98, v206 quad_perm:[1,0,3,2] row_mask:0xf bank_mask:0xf bound_ctrl:1
	v_add_f32_dpp v50, v50, v207 quad_perm:[1,0,3,2] row_mask:0xf bank_mask:0xf bound_ctrl:1
	v_xor_b32_e32 v200, v83, v51
	v_xor_b32_e32 v201, v83, v95
	v_xor_b32_e32 v202, v83, v94
	v_xor_b32_e32 v203, v83, v50
	v_add_f32_dpp v204, v51, v200 quad_perm:[2,3,0,1] row_mask:0xf bank_mask:0xf bound_ctrl:1
	v_add_f32_dpp v205, v95, v201 quad_perm:[2,3,0,1] row_mask:0xf bank_mask:0xf bound_ctrl:1
	v_add_f32_dpp v206, v94, v202 quad_perm:[2,3,0,1] row_mask:0xf bank_mask:0xf bound_ctrl:1
	v_add_f32_dpp v207, v50, v203 quad_perm:[2,3,0,1] row_mask:0xf bank_mask:0xf bound_ctrl:1
	v_xor_b32_e32 v200, v84, v204
	v_xor_b32_e32 v201, v84, v205
	v_xor_b32_e32 v202, v84, v206
	v_xor_b32_e32 v203, v84, v207
	v_add_f32_dpp v51, v204, v200 row_shl:4 row_mask:0xf bank_mask:0x5
	v_add_f32_dpp v95, v205, v201 row_shl:4 row_mask:0xf bank_mask:0x5
	v_add_f32_dpp v94, v206, v202 row_shl:4 row_mask:0xf bank_mask:0x5
	v_add_f32_dpp v96, v207, v203 row_shl:4 row_mask:0xf bank_mask:0x5
	v_add_f32_dpp v51, v204, v200 row_shr:4 row_mask:0xf bank_mask:0xa
	v_add_f32_dpp v95, v205, v201 row_shr:4 row_mask:0xf bank_mask:0xa
	v_add_f32_dpp v94, v206, v202 row_shr:4 row_mask:0xf bank_mask:0xa
	v_add_f32_dpp v96, v207, v203 row_shr:4 row_mask:0xf bank_mask:0xa
	v_max_f32_e64 v50, |v51|, |v95|
	v_max_f32_e64 v98, |v94|, |v96|
	v_max3_f32 v97, v97, v50, v98
	v_cvt_pk_bf16_f32 v50, v51, v95
	v_cvt_pk_bf16_f32 v51, v94, v96
	v_lshlrev_b32_e32 v94, 16, v48
	v_and_b32_e32 v48, 0xffff0000, v48
	v_lshlrev_b32_e32 v95, 16, v49
	v_and_b32_e32 v49, 0xffff0000, v49
	v_add_f32_e32 v96, v94, v48
	v_sub_f32_e32 v48, v94, v48
	v_add_f32_e32 v94, v95, v49
	v_sub_f32_e32 v49, v95, v49
	v_add_f32_e32 v95, v96, v94
	v_sub_f32_e32 v94, v96, v94
	v_add_f32_e32 v98, v48, v49
	v_sub_f32_e32 v48, v48, v49
	v_xor_b32_e32 v204, v82, v95
	v_xor_b32_e32 v205, v82, v94
	v_xor_b32_e32 v206, v82, v98
	v_xor_b32_e32 v207, v82, v48
	v_add_f32_dpp v49, v95, v204 quad_perm:[1,0,3,2] row_mask:0xf bank_mask:0xf bound_ctrl:1
	v_add_f32_dpp v94, v94, v205 quad_perm:[1,0,3,2] row_mask:0xf bank_mask:0xf bound_ctrl:1
	v_add_f32_dpp v95, v98, v206 quad_perm:[1,0,3,2] row_mask:0xf bank_mask:0xf bound_ctrl:1
	v_add_f32_dpp v48, v48, v207 quad_perm:[1,0,3,2] row_mask:0xf bank_mask:0xf bound_ctrl:1
	v_xor_b32_e32 v200, v83, v49
	v_xor_b32_e32 v201, v83, v95
	v_xor_b32_e32 v202, v83, v94
	v_xor_b32_e32 v203, v83, v48
	v_add_f32_dpp v204, v49, v200 quad_perm:[2,3,0,1] row_mask:0xf bank_mask:0xf bound_ctrl:1
	v_add_f32_dpp v205, v95, v201 quad_perm:[2,3,0,1] row_mask:0xf bank_mask:0xf bound_ctrl:1
	v_add_f32_dpp v206, v94, v202 quad_perm:[2,3,0,1] row_mask:0xf bank_mask:0xf bound_ctrl:1
	v_add_f32_dpp v207, v48, v203 quad_perm:[2,3,0,1] row_mask:0xf bank_mask:0xf bound_ctrl:1
	v_xor_b32_e32 v200, v84, v204
	v_xor_b32_e32 v201, v84, v205
	v_xor_b32_e32 v202, v84, v206
	v_xor_b32_e32 v203, v84, v207
	v_add_f32_dpp v49, v204, v200 row_shl:4 row_mask:0xf bank_mask:0x5
	v_add_f32_dpp v95, v205, v201 row_shl:4 row_mask:0xf bank_mask:0x5
	v_add_f32_dpp v94, v206, v202 row_shl:4 row_mask:0xf bank_mask:0x5
	v_add_f32_dpp v96, v207, v203 row_shl:4 row_mask:0xf bank_mask:0x5
	v_add_f32_dpp v49, v204, v200 row_shr:4 row_mask:0xf bank_mask:0xa
	v_add_f32_dpp v95, v205, v201 row_shr:4 row_mask:0xf bank_mask:0xa
	v_add_f32_dpp v94, v206, v202 row_shr:4 row_mask:0xf bank_mask:0xa
	v_add_f32_dpp v96, v207, v203 row_shr:4 row_mask:0xf bank_mask:0xa
	v_max_f32_e64 v48, |v49|, |v95|
	v_max_f32_e64 v98, |v94|, |v96|
	v_max3_f32 v97, v97, v48, v98
	v_cvt_pk_bf16_f32 v48, v49, v95
	v_cvt_pk_bf16_f32 v49, v94, v96
	v_lshlrev_b32_e32 v94, 16, v46
	v_and_b32_e32 v46, 0xffff0000, v46
	v_lshlrev_b32_e32 v95, 16, v47
	v_and_b32_e32 v47, 0xffff0000, v47
	v_add_f32_e32 v96, v94, v46
	v_sub_f32_e32 v46, v94, v46
	v_add_f32_e32 v94, v95, v47
	v_sub_f32_e32 v47, v95, v47
	v_add_f32_e32 v95, v96, v94
	v_sub_f32_e32 v94, v96, v94
	v_add_f32_e32 v98, v46, v47
	v_sub_f32_e32 v46, v46, v47
	v_xor_b32_e32 v204, v82, v95
	v_xor_b32_e32 v205, v82, v94
	v_xor_b32_e32 v206, v82, v98
	v_xor_b32_e32 v207, v82, v46
	v_add_f32_dpp v47, v95, v204 quad_perm:[1,0,3,2] row_mask:0xf bank_mask:0xf bound_ctrl:1
	v_add_f32_dpp v94, v94, v205 quad_perm:[1,0,3,2] row_mask:0xf bank_mask:0xf bound_ctrl:1
	v_add_f32_dpp v95, v98, v206 quad_perm:[1,0,3,2] row_mask:0xf bank_mask:0xf bound_ctrl:1
	v_add_f32_dpp v46, v46, v207 quad_perm:[1,0,3,2] row_mask:0xf bank_mask:0xf bound_ctrl:1
	v_xor_b32_e32 v200, v83, v47
	v_xor_b32_e32 v201, v83, v95
	v_xor_b32_e32 v202, v83, v94
	v_xor_b32_e32 v203, v83, v46
	v_add_f32_dpp v204, v47, v200 quad_perm:[2,3,0,1] row_mask:0xf bank_mask:0xf bound_ctrl:1
	v_add_f32_dpp v205, v95, v201 quad_perm:[2,3,0,1] row_mask:0xf bank_mask:0xf bound_ctrl:1
	v_add_f32_dpp v206, v94, v202 quad_perm:[2,3,0,1] row_mask:0xf bank_mask:0xf bound_ctrl:1
	v_add_f32_dpp v207, v46, v203 quad_perm:[2,3,0,1] row_mask:0xf bank_mask:0xf bound_ctrl:1
	v_xor_b32_e32 v200, v84, v204
	v_xor_b32_e32 v201, v84, v205
	v_xor_b32_e32 v202, v84, v206
	v_xor_b32_e32 v203, v84, v207
	v_add_f32_dpp v47, v204, v200 row_shl:4 row_mask:0xf bank_mask:0x5
	v_add_f32_dpp v95, v205, v201 row_shl:4 row_mask:0xf bank_mask:0x5
	v_add_f32_dpp v94, v206, v202 row_shl:4 row_mask:0xf bank_mask:0x5
	v_add_f32_dpp v96, v207, v203 row_shl:4 row_mask:0xf bank_mask:0x5
	v_add_f32_dpp v47, v204, v200 row_shr:4 row_mask:0xf bank_mask:0xa
	v_add_f32_dpp v95, v205, v201 row_shr:4 row_mask:0xf bank_mask:0xa
	v_add_f32_dpp v94, v206, v202 row_shr:4 row_mask:0xf bank_mask:0xa
	v_add_f32_dpp v96, v207, v203 row_shr:4 row_mask:0xf bank_mask:0xa
	v_max_f32_e64 v46, |v47|, |v95|
	v_max_f32_e64 v98, |v94|, |v96|
	v_max3_f32 v97, v97, v46, v98
	v_cvt_pk_bf16_f32 v46, v47, v95
	v_cvt_pk_bf16_f32 v47, v94, v96
	v_lshlrev_b32_e32 v94, 16, v44
	v_and_b32_e32 v44, 0xffff0000, v44
	v_lshlrev_b32_e32 v95, 16, v45
	v_and_b32_e32 v45, 0xffff0000, v45
	v_add_f32_e32 v96, v94, v44
	v_sub_f32_e32 v44, v94, v44
	v_add_f32_e32 v94, v95, v45
	v_sub_f32_e32 v45, v95, v45
	v_add_f32_e32 v95, v96, v94
	v_sub_f32_e32 v94, v96, v94
	v_add_f32_e32 v98, v44, v45
	v_sub_f32_e32 v44, v44, v45
	v_xor_b32_e32 v204, v82, v95
	v_xor_b32_e32 v205, v82, v94
	v_xor_b32_e32 v206, v82, v98
	v_xor_b32_e32 v207, v82, v44
	v_add_f32_dpp v45, v95, v204 quad_perm:[1,0,3,2] row_mask:0xf bank_mask:0xf bound_ctrl:1
	v_add_f32_dpp v94, v94, v205 quad_perm:[1,0,3,2] row_mask:0xf bank_mask:0xf bound_ctrl:1
	v_add_f32_dpp v95, v98, v206 quad_perm:[1,0,3,2] row_mask:0xf bank_mask:0xf bound_ctrl:1
	v_add_f32_dpp v44, v44, v207 quad_perm:[1,0,3,2] row_mask:0xf bank_mask:0xf bound_ctrl:1
	v_xor_b32_e32 v200, v83, v45
	v_xor_b32_e32 v201, v83, v95
	v_xor_b32_e32 v202, v83, v94
	v_xor_b32_e32 v203, v83, v44
	v_add_f32_dpp v204, v45, v200 quad_perm:[2,3,0,1] row_mask:0xf bank_mask:0xf bound_ctrl:1
	v_add_f32_dpp v205, v95, v201 quad_perm:[2,3,0,1] row_mask:0xf bank_mask:0xf bound_ctrl:1
	v_add_f32_dpp v206, v94, v202 quad_perm:[2,3,0,1] row_mask:0xf bank_mask:0xf bound_ctrl:1
	v_add_f32_dpp v207, v44, v203 quad_perm:[2,3,0,1] row_mask:0xf bank_mask:0xf bound_ctrl:1
	v_xor_b32_e32 v200, v84, v204
	v_xor_b32_e32 v201, v84, v205
	v_xor_b32_e32 v202, v84, v206
	v_xor_b32_e32 v203, v84, v207
	v_add_f32_dpp v45, v204, v200 row_shl:4 row_mask:0xf bank_mask:0x5
	v_add_f32_dpp v95, v205, v201 row_shl:4 row_mask:0xf bank_mask:0x5
	v_add_f32_dpp v94, v206, v202 row_shl:4 row_mask:0xf bank_mask:0x5
	v_add_f32_dpp v96, v207, v203 row_shl:4 row_mask:0xf bank_mask:0x5
	v_add_f32_dpp v45, v204, v200 row_shr:4 row_mask:0xf bank_mask:0xa
	v_add_f32_dpp v95, v205, v201 row_shr:4 row_mask:0xf bank_mask:0xa
	v_add_f32_dpp v94, v206, v202 row_shr:4 row_mask:0xf bank_mask:0xa
	v_add_f32_dpp v96, v207, v203 row_shr:4 row_mask:0xf bank_mask:0xa
	v_max_f32_e64 v44, |v45|, |v95|
	v_max_f32_e64 v98, |v94|, |v96|
	v_max3_f32 v97, v97, v44, v98
	v_cvt_pk_bf16_f32 v44, v45, v95
	v_cvt_pk_bf16_f32 v45, v94, v96
	v_lshlrev_b32_e32 v94, 16, v42
	v_and_b32_e32 v42, 0xffff0000, v42
	v_lshlrev_b32_e32 v95, 16, v43
	v_and_b32_e32 v43, 0xffff0000, v43
	v_add_f32_e32 v96, v94, v42
	v_sub_f32_e32 v42, v94, v42
	v_add_f32_e32 v94, v95, v43
	v_sub_f32_e32 v43, v95, v43
	v_add_f32_e32 v95, v96, v94
	v_sub_f32_e32 v94, v96, v94
	v_add_f32_e32 v98, v42, v43
	v_sub_f32_e32 v42, v42, v43
	v_xor_b32_e32 v204, v82, v95
	v_xor_b32_e32 v205, v82, v94
	v_xor_b32_e32 v206, v82, v98
	v_xor_b32_e32 v207, v82, v42
	v_add_f32_dpp v43, v95, v204 quad_perm:[1,0,3,2] row_mask:0xf bank_mask:0xf bound_ctrl:1
	v_add_f32_dpp v94, v94, v205 quad_perm:[1,0,3,2] row_mask:0xf bank_mask:0xf bound_ctrl:1
	v_add_f32_dpp v95, v98, v206 quad_perm:[1,0,3,2] row_mask:0xf bank_mask:0xf bound_ctrl:1
	v_add_f32_dpp v42, v42, v207 quad_perm:[1,0,3,2] row_mask:0xf bank_mask:0xf bound_ctrl:1
	v_xor_b32_e32 v200, v83, v43
	v_xor_b32_e32 v201, v83, v95
	v_xor_b32_e32 v202, v83, v94
	v_xor_b32_e32 v203, v83, v42
	v_add_f32_dpp v204, v43, v200 quad_perm:[2,3,0,1] row_mask:0xf bank_mask:0xf bound_ctrl:1
	v_add_f32_dpp v205, v95, v201 quad_perm:[2,3,0,1] row_mask:0xf bank_mask:0xf bound_ctrl:1
	v_add_f32_dpp v206, v94, v202 quad_perm:[2,3,0,1] row_mask:0xf bank_mask:0xf bound_ctrl:1
	v_add_f32_dpp v207, v42, v203 quad_perm:[2,3,0,1] row_mask:0xf bank_mask:0xf bound_ctrl:1
	v_xor_b32_e32 v200, v84, v204
	v_xor_b32_e32 v201, v84, v205
	v_xor_b32_e32 v202, v84, v206
	v_xor_b32_e32 v203, v84, v207
	v_add_f32_dpp v43, v204, v200 row_shl:4 row_mask:0xf bank_mask:0x5
	v_add_f32_dpp v95, v205, v201 row_shl:4 row_mask:0xf bank_mask:0x5
	v_add_f32_dpp v94, v206, v202 row_shl:4 row_mask:0xf bank_mask:0x5
	v_add_f32_dpp v96, v207, v203 row_shl:4 row_mask:0xf bank_mask:0x5
	v_add_f32_dpp v43, v204, v200 row_shr:4 row_mask:0xf bank_mask:0xa
	v_add_f32_dpp v95, v205, v201 row_shr:4 row_mask:0xf bank_mask:0xa
	v_add_f32_dpp v94, v206, v202 row_shr:4 row_mask:0xf bank_mask:0xa
	v_add_f32_dpp v96, v207, v203 row_shr:4 row_mask:0xf bank_mask:0xa
	v_max_f32_e64 v42, |v43|, |v95|
	v_max_f32_e64 v98, |v94|, |v96|
	v_max3_f32 v97, v97, v42, v98
	v_cvt_pk_bf16_f32 v42, v43, v95
	v_cvt_pk_bf16_f32 v43, v94, v96
	v_lshlrev_b32_e32 v94, 16, v40
	v_and_b32_e32 v40, 0xffff0000, v40
	v_lshlrev_b32_e32 v95, 16, v41
	v_and_b32_e32 v41, 0xffff0000, v41
	v_add_f32_e32 v96, v94, v40
	v_sub_f32_e32 v40, v94, v40
	v_add_f32_e32 v94, v95, v41
	v_sub_f32_e32 v41, v95, v41
	v_add_f32_e32 v95, v96, v94
	v_sub_f32_e32 v94, v96, v94
	v_add_f32_e32 v98, v40, v41
	v_sub_f32_e32 v40, v40, v41
	v_xor_b32_e32 v204, v82, v95
	v_xor_b32_e32 v205, v82, v94
	v_xor_b32_e32 v206, v82, v98
	v_xor_b32_e32 v207, v82, v40
	v_add_f32_dpp v41, v95, v204 quad_perm:[1,0,3,2] row_mask:0xf bank_mask:0xf bound_ctrl:1
	v_add_f32_dpp v94, v94, v205 quad_perm:[1,0,3,2] row_mask:0xf bank_mask:0xf bound_ctrl:1
	v_add_f32_dpp v95, v98, v206 quad_perm:[1,0,3,2] row_mask:0xf bank_mask:0xf bound_ctrl:1
	v_add_f32_dpp v40, v40, v207 quad_perm:[1,0,3,2] row_mask:0xf bank_mask:0xf bound_ctrl:1
	v_xor_b32_e32 v200, v83, v41
	v_xor_b32_e32 v201, v83, v95
	v_xor_b32_e32 v202, v83, v94
	v_xor_b32_e32 v203, v83, v40
	v_add_f32_dpp v204, v41, v200 quad_perm:[2,3,0,1] row_mask:0xf bank_mask:0xf bound_ctrl:1
	v_add_f32_dpp v205, v95, v201 quad_perm:[2,3,0,1] row_mask:0xf bank_mask:0xf bound_ctrl:1
	v_add_f32_dpp v206, v94, v202 quad_perm:[2,3,0,1] row_mask:0xf bank_mask:0xf bound_ctrl:1
	v_add_f32_dpp v207, v40, v203 quad_perm:[2,3,0,1] row_mask:0xf bank_mask:0xf bound_ctrl:1
	v_xor_b32_e32 v200, v84, v204
	v_xor_b32_e32 v201, v84, v205
	v_xor_b32_e32 v202, v84, v206
	v_xor_b32_e32 v203, v84, v207
	v_add_f32_dpp v41, v204, v200 row_shl:4 row_mask:0xf bank_mask:0x5
	v_add_f32_dpp v95, v205, v201 row_shl:4 row_mask:0xf bank_mask:0x5
	v_add_f32_dpp v94, v206, v202 row_shl:4 row_mask:0xf bank_mask:0x5
	v_add_f32_dpp v96, v207, v203 row_shl:4 row_mask:0xf bank_mask:0x5
	v_add_f32_dpp v41, v204, v200 row_shr:4 row_mask:0xf bank_mask:0xa
	v_add_f32_dpp v95, v205, v201 row_shr:4 row_mask:0xf bank_mask:0xa
	v_add_f32_dpp v94, v206, v202 row_shr:4 row_mask:0xf bank_mask:0xa
	v_add_f32_dpp v96, v207, v203 row_shr:4 row_mask:0xf bank_mask:0xa
	v_max_f32_e64 v40, |v41|, |v95|
	v_max_f32_e64 v98, |v94|, |v96|
	v_max3_f32 v97, v97, v40, v98
	v_cvt_pk_bf16_f32 v40, v41, v95
	v_cvt_pk_bf16_f32 v41, v94, v96
	v_lshlrev_b32_e32 v94, 16, v38
	v_and_b32_e32 v38, 0xffff0000, v38
	v_lshlrev_b32_e32 v95, 16, v39
	v_and_b32_e32 v39, 0xffff0000, v39
	v_add_f32_e32 v96, v94, v38
	v_sub_f32_e32 v38, v94, v38
	v_add_f32_e32 v94, v95, v39
	v_sub_f32_e32 v39, v95, v39
	v_add_f32_e32 v95, v96, v94
	v_sub_f32_e32 v94, v96, v94
	v_add_f32_e32 v98, v38, v39
	v_sub_f32_e32 v38, v38, v39
	v_xor_b32_e32 v204, v82, v95
	v_xor_b32_e32 v205, v82, v94
	v_xor_b32_e32 v206, v82, v98
	v_xor_b32_e32 v207, v82, v38
	v_add_f32_dpp v39, v95, v204 quad_perm:[1,0,3,2] row_mask:0xf bank_mask:0xf bound_ctrl:1
	v_add_f32_dpp v94, v94, v205 quad_perm:[1,0,3,2] row_mask:0xf bank_mask:0xf bound_ctrl:1
	v_add_f32_dpp v95, v98, v206 quad_perm:[1,0,3,2] row_mask:0xf bank_mask:0xf bound_ctrl:1
	v_add_f32_dpp v38, v38, v207 quad_perm:[1,0,3,2] row_mask:0xf bank_mask:0xf bound_ctrl:1
	v_xor_b32_e32 v200, v83, v39
	v_xor_b32_e32 v201, v83, v95
	v_xor_b32_e32 v202, v83, v94
	v_xor_b32_e32 v203, v83, v38
	v_add_f32_dpp v204, v39, v200 quad_perm:[2,3,0,1] row_mask:0xf bank_mask:0xf bound_ctrl:1
	v_add_f32_dpp v205, v95, v201 quad_perm:[2,3,0,1] row_mask:0xf bank_mask:0xf bound_ctrl:1
	v_add_f32_dpp v206, v94, v202 quad_perm:[2,3,0,1] row_mask:0xf bank_mask:0xf bound_ctrl:1
	v_add_f32_dpp v207, v38, v203 quad_perm:[2,3,0,1] row_mask:0xf bank_mask:0xf bound_ctrl:1
	v_xor_b32_e32 v200, v84, v204
	v_xor_b32_e32 v201, v84, v205
	v_xor_b32_e32 v202, v84, v206
	v_xor_b32_e32 v203, v84, v207
	v_add_f32_dpp v39, v204, v200 row_shl:4 row_mask:0xf bank_mask:0x5
	v_add_f32_dpp v95, v205, v201 row_shl:4 row_mask:0xf bank_mask:0x5
	v_add_f32_dpp v94, v206, v202 row_shl:4 row_mask:0xf bank_mask:0x5
	v_add_f32_dpp v96, v207, v203 row_shl:4 row_mask:0xf bank_mask:0x5
	v_add_f32_dpp v39, v204, v200 row_shr:4 row_mask:0xf bank_mask:0xa
	v_add_f32_dpp v95, v205, v201 row_shr:4 row_mask:0xf bank_mask:0xa
	v_add_f32_dpp v94, v206, v202 row_shr:4 row_mask:0xf bank_mask:0xa
	v_add_f32_dpp v96, v207, v203 row_shr:4 row_mask:0xf bank_mask:0xa
	v_max_f32_e64 v38, |v39|, |v95|
	v_max_f32_e64 v98, |v94|, |v96|
	v_max3_f32 v97, v97, v38, v98
	v_cvt_pk_bf16_f32 v38, v39, v95
	v_cvt_pk_bf16_f32 v39, v94, v96
	v_lshlrev_b32_e32 v94, 16, v36
	v_and_b32_e32 v36, 0xffff0000, v36
	v_lshlrev_b32_e32 v95, 16, v37
	v_and_b32_e32 v37, 0xffff0000, v37
	v_add_f32_e32 v96, v94, v36
	v_sub_f32_e32 v36, v94, v36
	v_add_f32_e32 v94, v95, v37
	v_sub_f32_e32 v37, v95, v37
	v_add_f32_e32 v95, v96, v94
	v_sub_f32_e32 v94, v96, v94
	v_add_f32_e32 v98, v36, v37
	v_sub_f32_e32 v36, v36, v37
	v_xor_b32_e32 v204, v82, v95
	v_xor_b32_e32 v205, v82, v94
	v_xor_b32_e32 v206, v82, v98
	v_xor_b32_e32 v207, v82, v36
	v_add_f32_dpp v37, v95, v204 quad_perm:[1,0,3,2] row_mask:0xf bank_mask:0xf bound_ctrl:1
	v_add_f32_dpp v94, v94, v205 quad_perm:[1,0,3,2] row_mask:0xf bank_mask:0xf bound_ctrl:1
	v_add_f32_dpp v95, v98, v206 quad_perm:[1,0,3,2] row_mask:0xf bank_mask:0xf bound_ctrl:1
	v_add_f32_dpp v36, v36, v207 quad_perm:[1,0,3,2] row_mask:0xf bank_mask:0xf bound_ctrl:1
	v_xor_b32_e32 v200, v83, v37
	v_xor_b32_e32 v201, v83, v95
	v_xor_b32_e32 v202, v83, v94
	v_xor_b32_e32 v203, v83, v36
	v_add_f32_dpp v204, v37, v200 quad_perm:[2,3,0,1] row_mask:0xf bank_mask:0xf bound_ctrl:1
	v_add_f32_dpp v205, v95, v201 quad_perm:[2,3,0,1] row_mask:0xf bank_mask:0xf bound_ctrl:1
	v_add_f32_dpp v206, v94, v202 quad_perm:[2,3,0,1] row_mask:0xf bank_mask:0xf bound_ctrl:1
	v_add_f32_dpp v207, v36, v203 quad_perm:[2,3,0,1] row_mask:0xf bank_mask:0xf bound_ctrl:1
	v_xor_b32_e32 v200, v84, v204
	v_xor_b32_e32 v201, v84, v205
	v_xor_b32_e32 v202, v84, v206
	v_xor_b32_e32 v203, v84, v207
	v_add_f32_dpp v37, v204, v200 row_shl:4 row_mask:0xf bank_mask:0x5
	v_add_f32_dpp v95, v205, v201 row_shl:4 row_mask:0xf bank_mask:0x5
	v_add_f32_dpp v94, v206, v202 row_shl:4 row_mask:0xf bank_mask:0x5
	v_add_f32_dpp v96, v207, v203 row_shl:4 row_mask:0xf bank_mask:0x5
	v_add_f32_dpp v37, v204, v200 row_shr:4 row_mask:0xf bank_mask:0xa
	v_add_f32_dpp v95, v205, v201 row_shr:4 row_mask:0xf bank_mask:0xa
	v_add_f32_dpp v94, v206, v202 row_shr:4 row_mask:0xf bank_mask:0xa
	v_add_f32_dpp v96, v207, v203 row_shr:4 row_mask:0xf bank_mask:0xa
	v_max_f32_e64 v36, |v37|, |v95|
	v_max_f32_e64 v98, |v94|, |v96|
	v_max3_f32 v97, v97, v36, v98
	v_cvt_pk_bf16_f32 v36, v37, v95
	v_cvt_pk_bf16_f32 v37, v94, v96
	v_lshlrev_b32_e32 v94, 16, v34
	v_and_b32_e32 v34, 0xffff0000, v34
	v_lshlrev_b32_e32 v95, 16, v35
	v_and_b32_e32 v35, 0xffff0000, v35
	v_add_f32_e32 v96, v94, v34
	v_sub_f32_e32 v34, v94, v34
	v_add_f32_e32 v94, v95, v35
	v_sub_f32_e32 v35, v95, v35
	v_add_f32_e32 v95, v96, v94
	v_sub_f32_e32 v94, v96, v94
	v_add_f32_e32 v98, v34, v35
	v_sub_f32_e32 v34, v34, v35
	v_xor_b32_e32 v204, v82, v95
	v_xor_b32_e32 v205, v82, v94
	v_xor_b32_e32 v206, v82, v98
	v_xor_b32_e32 v207, v82, v34
	v_add_f32_dpp v35, v95, v204 quad_perm:[1,0,3,2] row_mask:0xf bank_mask:0xf bound_ctrl:1
	v_add_f32_dpp v94, v94, v205 quad_perm:[1,0,3,2] row_mask:0xf bank_mask:0xf bound_ctrl:1
	v_add_f32_dpp v95, v98, v206 quad_perm:[1,0,3,2] row_mask:0xf bank_mask:0xf bound_ctrl:1
	v_add_f32_dpp v34, v34, v207 quad_perm:[1,0,3,2] row_mask:0xf bank_mask:0xf bound_ctrl:1
	v_xor_b32_e32 v200, v83, v35
	v_xor_b32_e32 v201, v83, v95
	v_xor_b32_e32 v202, v83, v94
	v_xor_b32_e32 v203, v83, v34
	v_add_f32_dpp v204, v35, v200 quad_perm:[2,3,0,1] row_mask:0xf bank_mask:0xf bound_ctrl:1
	v_add_f32_dpp v205, v95, v201 quad_perm:[2,3,0,1] row_mask:0xf bank_mask:0xf bound_ctrl:1
	v_add_f32_dpp v206, v94, v202 quad_perm:[2,3,0,1] row_mask:0xf bank_mask:0xf bound_ctrl:1
	v_add_f32_dpp v207, v34, v203 quad_perm:[2,3,0,1] row_mask:0xf bank_mask:0xf bound_ctrl:1
	v_xor_b32_e32 v200, v84, v204
	v_xor_b32_e32 v201, v84, v205
	v_xor_b32_e32 v202, v84, v206
	v_xor_b32_e32 v203, v84, v207
	v_add_f32_dpp v35, v204, v200 row_shl:4 row_mask:0xf bank_mask:0x5
	v_add_f32_dpp v95, v205, v201 row_shl:4 row_mask:0xf bank_mask:0x5
	v_add_f32_dpp v94, v206, v202 row_shl:4 row_mask:0xf bank_mask:0x5
	v_add_f32_dpp v96, v207, v203 row_shl:4 row_mask:0xf bank_mask:0x5
	v_add_f32_dpp v35, v204, v200 row_shr:4 row_mask:0xf bank_mask:0xa
	v_add_f32_dpp v95, v205, v201 row_shr:4 row_mask:0xf bank_mask:0xa
	v_add_f32_dpp v94, v206, v202 row_shr:4 row_mask:0xf bank_mask:0xa
	v_add_f32_dpp v96, v207, v203 row_shr:4 row_mask:0xf bank_mask:0xa
	v_max_f32_e64 v34, |v35|, |v95|
	v_max_f32_e64 v98, |v94|, |v96|
	v_max3_f32 v97, v97, v34, v98
	v_cvt_pk_bf16_f32 v34, v35, v95
	v_cvt_pk_bf16_f32 v35, v94, v96
	v_lshlrev_b32_e32 v94, 16, v32
	v_and_b32_e32 v32, 0xffff0000, v32
	v_lshlrev_b32_e32 v95, 16, v33
	v_and_b32_e32 v33, 0xffff0000, v33
	v_add_f32_e32 v96, v94, v32
	v_sub_f32_e32 v32, v94, v32
	v_add_f32_e32 v94, v95, v33
	v_sub_f32_e32 v33, v95, v33
	v_add_f32_e32 v95, v96, v94
	v_sub_f32_e32 v94, v96, v94
	v_add_f32_e32 v98, v32, v33
	v_sub_f32_e32 v32, v32, v33
	v_xor_b32_e32 v204, v82, v95
	v_xor_b32_e32 v205, v82, v94
	v_xor_b32_e32 v206, v82, v98
	v_xor_b32_e32 v207, v82, v32
	v_add_f32_dpp v33, v95, v204 quad_perm:[1,0,3,2] row_mask:0xf bank_mask:0xf bound_ctrl:1
	v_add_f32_dpp v94, v94, v205 quad_perm:[1,0,3,2] row_mask:0xf bank_mask:0xf bound_ctrl:1
	v_add_f32_dpp v95, v98, v206 quad_perm:[1,0,3,2] row_mask:0xf bank_mask:0xf bound_ctrl:1
	v_add_f32_dpp v32, v32, v207 quad_perm:[1,0,3,2] row_mask:0xf bank_mask:0xf bound_ctrl:1
	v_xor_b32_e32 v200, v83, v33
	v_xor_b32_e32 v201, v83, v95
	v_xor_b32_e32 v202, v83, v94
	v_xor_b32_e32 v203, v83, v32
	v_add_f32_dpp v204, v33, v200 quad_perm:[2,3,0,1] row_mask:0xf bank_mask:0xf bound_ctrl:1
	v_add_f32_dpp v205, v95, v201 quad_perm:[2,3,0,1] row_mask:0xf bank_mask:0xf bound_ctrl:1
	v_add_f32_dpp v206, v94, v202 quad_perm:[2,3,0,1] row_mask:0xf bank_mask:0xf bound_ctrl:1
	v_add_f32_dpp v207, v32, v203 quad_perm:[2,3,0,1] row_mask:0xf bank_mask:0xf bound_ctrl:1
	v_xor_b32_e32 v200, v84, v204
	v_xor_b32_e32 v201, v84, v205
	v_xor_b32_e32 v202, v84, v206
	v_xor_b32_e32 v203, v84, v207
	v_add_f32_dpp v33, v204, v200 row_shl:4 row_mask:0xf bank_mask:0x5
	v_add_f32_dpp v95, v205, v201 row_shl:4 row_mask:0xf bank_mask:0x5
	v_add_f32_dpp v94, v206, v202 row_shl:4 row_mask:0xf bank_mask:0x5
	v_add_f32_dpp v96, v207, v203 row_shl:4 row_mask:0xf bank_mask:0x5
	v_add_f32_dpp v33, v204, v200 row_shr:4 row_mask:0xf bank_mask:0xa
	v_add_f32_dpp v95, v205, v201 row_shr:4 row_mask:0xf bank_mask:0xa
	v_add_f32_dpp v94, v206, v202 row_shr:4 row_mask:0xf bank_mask:0xa
	v_add_f32_dpp v96, v207, v203 row_shr:4 row_mask:0xf bank_mask:0xa
	v_max_f32_e64 v32, |v33|, |v95|
	v_max_f32_e64 v98, |v94|, |v96|
	v_max3_f32 v97, v97, v32, v98
	v_cvt_pk_bf16_f32 v32, v33, v95
	v_cvt_pk_bf16_f32 v33, v94, v96
	v_lshlrev_b32_e32 v94, 16, v30
	v_and_b32_e32 v30, 0xffff0000, v30
	v_lshlrev_b32_e32 v95, 16, v31
	v_and_b32_e32 v31, 0xffff0000, v31
	v_add_f32_e32 v96, v94, v30
	v_sub_f32_e32 v30, v94, v30
	v_add_f32_e32 v94, v95, v31
	v_sub_f32_e32 v31, v95, v31
	v_add_f32_e32 v95, v96, v94
	v_sub_f32_e32 v94, v96, v94
	v_add_f32_e32 v98, v30, v31
	v_sub_f32_e32 v30, v30, v31
	v_xor_b32_e32 v204, v82, v95
	v_xor_b32_e32 v205, v82, v94
	v_xor_b32_e32 v206, v82, v98
	v_xor_b32_e32 v207, v82, v30
	v_add_f32_dpp v31, v95, v204 quad_perm:[1,0,3,2] row_mask:0xf bank_mask:0xf bound_ctrl:1
	v_add_f32_dpp v94, v94, v205 quad_perm:[1,0,3,2] row_mask:0xf bank_mask:0xf bound_ctrl:1
	v_add_f32_dpp v95, v98, v206 quad_perm:[1,0,3,2] row_mask:0xf bank_mask:0xf bound_ctrl:1
	v_add_f32_dpp v30, v30, v207 quad_perm:[1,0,3,2] row_mask:0xf bank_mask:0xf bound_ctrl:1
	v_xor_b32_e32 v200, v83, v31
	v_xor_b32_e32 v201, v83, v95
	v_xor_b32_e32 v202, v83, v94
	v_xor_b32_e32 v203, v83, v30
	v_add_f32_dpp v204, v31, v200 quad_perm:[2,3,0,1] row_mask:0xf bank_mask:0xf bound_ctrl:1
	v_add_f32_dpp v205, v95, v201 quad_perm:[2,3,0,1] row_mask:0xf bank_mask:0xf bound_ctrl:1
	v_add_f32_dpp v206, v94, v202 quad_perm:[2,3,0,1] row_mask:0xf bank_mask:0xf bound_ctrl:1
	v_add_f32_dpp v207, v30, v203 quad_perm:[2,3,0,1] row_mask:0xf bank_mask:0xf bound_ctrl:1
	v_xor_b32_e32 v200, v84, v204
	v_xor_b32_e32 v201, v84, v205
	v_xor_b32_e32 v202, v84, v206
	v_xor_b32_e32 v203, v84, v207
	v_add_f32_dpp v31, v204, v200 row_shl:4 row_mask:0xf bank_mask:0x5
	v_add_f32_dpp v95, v205, v201 row_shl:4 row_mask:0xf bank_mask:0x5
	v_add_f32_dpp v94, v206, v202 row_shl:4 row_mask:0xf bank_mask:0x5
	v_add_f32_dpp v96, v207, v203 row_shl:4 row_mask:0xf bank_mask:0x5
	v_add_f32_dpp v31, v204, v200 row_shr:4 row_mask:0xf bank_mask:0xa
	v_add_f32_dpp v95, v205, v201 row_shr:4 row_mask:0xf bank_mask:0xa
	v_add_f32_dpp v94, v206, v202 row_shr:4 row_mask:0xf bank_mask:0xa
	v_add_f32_dpp v96, v207, v203 row_shr:4 row_mask:0xf bank_mask:0xa
	v_max_f32_e64 v30, |v31|, |v95|
	v_max_f32_e64 v98, |v94|, |v96|
	v_max3_f32 v97, v97, v30, v98
	v_cvt_pk_bf16_f32 v30, v31, v95
	v_cvt_pk_bf16_f32 v31, v94, v96
	v_lshlrev_b32_e32 v94, 16, v28
	v_and_b32_e32 v28, 0xffff0000, v28
	v_lshlrev_b32_e32 v95, 16, v29
	v_and_b32_e32 v29, 0xffff0000, v29
	v_add_f32_e32 v96, v94, v28
	v_sub_f32_e32 v28, v94, v28
	v_add_f32_e32 v94, v95, v29
	v_sub_f32_e32 v29, v95, v29
	v_add_f32_e32 v95, v96, v94
	v_sub_f32_e32 v94, v96, v94
	v_add_f32_e32 v98, v28, v29
	v_sub_f32_e32 v28, v28, v29
	v_xor_b32_e32 v204, v82, v95
	v_xor_b32_e32 v205, v82, v94
	v_xor_b32_e32 v206, v82, v98
	v_xor_b32_e32 v207, v82, v28
	v_add_f32_dpp v29, v95, v204 quad_perm:[1,0,3,2] row_mask:0xf bank_mask:0xf bound_ctrl:1
	v_add_f32_dpp v94, v94, v205 quad_perm:[1,0,3,2] row_mask:0xf bank_mask:0xf bound_ctrl:1
	v_add_f32_dpp v95, v98, v206 quad_perm:[1,0,3,2] row_mask:0xf bank_mask:0xf bound_ctrl:1
	v_add_f32_dpp v28, v28, v207 quad_perm:[1,0,3,2] row_mask:0xf bank_mask:0xf bound_ctrl:1
	v_xor_b32_e32 v200, v83, v29
	v_xor_b32_e32 v201, v83, v95
	v_xor_b32_e32 v202, v83, v94
	v_xor_b32_e32 v203, v83, v28
	v_add_f32_dpp v204, v29, v200 quad_perm:[2,3,0,1] row_mask:0xf bank_mask:0xf bound_ctrl:1
	v_add_f32_dpp v205, v95, v201 quad_perm:[2,3,0,1] row_mask:0xf bank_mask:0xf bound_ctrl:1
	v_add_f32_dpp v206, v94, v202 quad_perm:[2,3,0,1] row_mask:0xf bank_mask:0xf bound_ctrl:1
	v_add_f32_dpp v207, v28, v203 quad_perm:[2,3,0,1] row_mask:0xf bank_mask:0xf bound_ctrl:1
	v_xor_b32_e32 v200, v84, v204
	v_xor_b32_e32 v201, v84, v205
	v_xor_b32_e32 v202, v84, v206
	v_xor_b32_e32 v203, v84, v207
	v_add_f32_dpp v29, v204, v200 row_shl:4 row_mask:0xf bank_mask:0x5
	v_add_f32_dpp v95, v205, v201 row_shl:4 row_mask:0xf bank_mask:0x5
	v_add_f32_dpp v94, v206, v202 row_shl:4 row_mask:0xf bank_mask:0x5
	v_add_f32_dpp v96, v207, v203 row_shl:4 row_mask:0xf bank_mask:0x5
	v_add_f32_dpp v29, v204, v200 row_shr:4 row_mask:0xf bank_mask:0xa
	v_add_f32_dpp v95, v205, v201 row_shr:4 row_mask:0xf bank_mask:0xa
	v_add_f32_dpp v94, v206, v202 row_shr:4 row_mask:0xf bank_mask:0xa
	v_add_f32_dpp v96, v207, v203 row_shr:4 row_mask:0xf bank_mask:0xa
	v_max_f32_e64 v28, |v29|, |v95|
	v_max_f32_e64 v98, |v94|, |v96|
	v_max3_f32 v97, v97, v28, v98
	v_cvt_pk_bf16_f32 v28, v29, v95
	v_cvt_pk_bf16_f32 v29, v94, v96
	v_lshlrev_b32_e32 v94, 16, v26
	v_and_b32_e32 v26, 0xffff0000, v26
	v_lshlrev_b32_e32 v95, 16, v27
	v_and_b32_e32 v27, 0xffff0000, v27
	v_add_f32_e32 v96, v94, v26
	v_sub_f32_e32 v26, v94, v26
	v_add_f32_e32 v94, v95, v27
	v_sub_f32_e32 v27, v95, v27
	v_add_f32_e32 v95, v96, v94
	v_sub_f32_e32 v94, v96, v94
	v_add_f32_e32 v98, v26, v27
	v_sub_f32_e32 v26, v26, v27
	v_xor_b32_e32 v204, v82, v95
	v_xor_b32_e32 v205, v82, v94
	v_xor_b32_e32 v206, v82, v98
	v_xor_b32_e32 v207, v82, v26
	v_add_f32_dpp v27, v95, v204 quad_perm:[1,0,3,2] row_mask:0xf bank_mask:0xf bound_ctrl:1
	v_add_f32_dpp v94, v94, v205 quad_perm:[1,0,3,2] row_mask:0xf bank_mask:0xf bound_ctrl:1
	v_add_f32_dpp v95, v98, v206 quad_perm:[1,0,3,2] row_mask:0xf bank_mask:0xf bound_ctrl:1
	v_add_f32_dpp v26, v26, v207 quad_perm:[1,0,3,2] row_mask:0xf bank_mask:0xf bound_ctrl:1
	v_xor_b32_e32 v200, v83, v27
	v_xor_b32_e32 v201, v83, v95
	v_xor_b32_e32 v202, v83, v94
	v_xor_b32_e32 v203, v83, v26
	v_add_f32_dpp v204, v27, v200 quad_perm:[2,3,0,1] row_mask:0xf bank_mask:0xf bound_ctrl:1
	v_add_f32_dpp v205, v95, v201 quad_perm:[2,3,0,1] row_mask:0xf bank_mask:0xf bound_ctrl:1
	v_add_f32_dpp v206, v94, v202 quad_perm:[2,3,0,1] row_mask:0xf bank_mask:0xf bound_ctrl:1
	v_add_f32_dpp v207, v26, v203 quad_perm:[2,3,0,1] row_mask:0xf bank_mask:0xf bound_ctrl:1
	v_xor_b32_e32 v200, v84, v204
	v_xor_b32_e32 v201, v84, v205
	v_xor_b32_e32 v202, v84, v206
	v_xor_b32_e32 v203, v84, v207
	v_add_f32_dpp v27, v204, v200 row_shl:4 row_mask:0xf bank_mask:0x5
	v_add_f32_dpp v95, v205, v201 row_shl:4 row_mask:0xf bank_mask:0x5
	v_add_f32_dpp v94, v206, v202 row_shl:4 row_mask:0xf bank_mask:0x5
	v_add_f32_dpp v96, v207, v203 row_shl:4 row_mask:0xf bank_mask:0x5
	v_add_f32_dpp v27, v204, v200 row_shr:4 row_mask:0xf bank_mask:0xa
	v_add_f32_dpp v95, v205, v201 row_shr:4 row_mask:0xf bank_mask:0xa
	v_add_f32_dpp v94, v206, v202 row_shr:4 row_mask:0xf bank_mask:0xa
	v_add_f32_dpp v96, v207, v203 row_shr:4 row_mask:0xf bank_mask:0xa
	v_max_f32_e64 v26, |v27|, |v95|
	v_max_f32_e64 v98, |v94|, |v96|
	v_max3_f32 v97, v97, v26, v98
	v_cvt_pk_bf16_f32 v26, v27, v95
	v_cvt_pk_bf16_f32 v27, v94, v96
	v_lshlrev_b32_e32 v94, 16, v24
	v_and_b32_e32 v24, 0xffff0000, v24
	v_lshlrev_b32_e32 v95, 16, v25
	v_and_b32_e32 v25, 0xffff0000, v25
	v_add_f32_e32 v96, v94, v24
	v_sub_f32_e32 v24, v94, v24
	v_add_f32_e32 v94, v95, v25
	v_sub_f32_e32 v25, v95, v25
	v_add_f32_e32 v95, v96, v94
	v_sub_f32_e32 v94, v96, v94
	v_add_f32_e32 v98, v24, v25
	v_sub_f32_e32 v24, v24, v25
	v_xor_b32_e32 v204, v82, v95
	v_xor_b32_e32 v205, v82, v94
	v_xor_b32_e32 v206, v82, v98
	v_xor_b32_e32 v207, v82, v24
	v_add_f32_dpp v25, v95, v204 quad_perm:[1,0,3,2] row_mask:0xf bank_mask:0xf bound_ctrl:1
	v_add_f32_dpp v94, v94, v205 quad_perm:[1,0,3,2] row_mask:0xf bank_mask:0xf bound_ctrl:1
	v_add_f32_dpp v95, v98, v206 quad_perm:[1,0,3,2] row_mask:0xf bank_mask:0xf bound_ctrl:1
	v_add_f32_dpp v24, v24, v207 quad_perm:[1,0,3,2] row_mask:0xf bank_mask:0xf bound_ctrl:1
	v_xor_b32_e32 v200, v83, v25
	v_xor_b32_e32 v201, v83, v95
	v_xor_b32_e32 v202, v83, v94
	v_xor_b32_e32 v203, v83, v24
	v_add_f32_dpp v204, v25, v200 quad_perm:[2,3,0,1] row_mask:0xf bank_mask:0xf bound_ctrl:1
	v_add_f32_dpp v205, v95, v201 quad_perm:[2,3,0,1] row_mask:0xf bank_mask:0xf bound_ctrl:1
	v_add_f32_dpp v206, v94, v202 quad_perm:[2,3,0,1] row_mask:0xf bank_mask:0xf bound_ctrl:1
	v_add_f32_dpp v207, v24, v203 quad_perm:[2,3,0,1] row_mask:0xf bank_mask:0xf bound_ctrl:1
	v_xor_b32_e32 v200, v84, v204
	v_xor_b32_e32 v201, v84, v205
	v_xor_b32_e32 v202, v84, v206
	v_xor_b32_e32 v203, v84, v207
	v_add_f32_dpp v24, v204, v200 row_shl:4 row_mask:0xf bank_mask:0x5
	v_add_f32_dpp v25, v205, v201 row_shl:4 row_mask:0xf bank_mask:0x5
	v_add_f32_dpp v94, v206, v202 row_shl:4 row_mask:0xf bank_mask:0x5
	v_add_f32_dpp v95, v207, v203 row_shl:4 row_mask:0xf bank_mask:0x5
	v_add_f32_dpp v24, v204, v200 row_shr:4 row_mask:0xf bank_mask:0xa
	v_add_f32_dpp v25, v205, v201 row_shr:4 row_mask:0xf bank_mask:0xa
	v_add_f32_dpp v94, v206, v202 row_shr:4 row_mask:0xf bank_mask:0xa
	v_add_f32_dpp v95, v207, v203 row_shr:4 row_mask:0xf bank_mask:0xa
	v_max_f32_e64 v96, |v24|, |v25|
	v_max_f32_e64 v98, |v94|, |v95|
	v_max3_f32 v98, v97, v96, v98
	v_lshlrev_b32_e32 v96, 16, v22
	v_and_b32_e32 v22, 0xffff0000, v22
	v_lshlrev_b32_e32 v97, 16, v23
	v_and_b32_e32 v23, 0xffff0000, v23
	v_add_f32_e32 v99, v96, v22
	v_sub_f32_e32 v22, v96, v22
	v_add_f32_e32 v96, v97, v23
	v_sub_f32_e32 v23, v97, v23
	v_add_f32_e32 v97, v99, v96
	v_sub_f32_e32 v96, v99, v96
	v_add_f32_e32 v100, v22, v23
	v_sub_f32_e32 v22, v22, v23
	v_xor_b32_e32 v204, v82, v97
	v_xor_b32_e32 v205, v82, v96
	v_xor_b32_e32 v206, v82, v100
	v_xor_b32_e32 v207, v82, v22
	v_cvt_pk_bf16_f32 v24, v24, v25
	v_cvt_pk_bf16_f32 v25, v94, v95
	v_add_f32_dpp v23, v97, v204 quad_perm:[1,0,3,2] row_mask:0xf bank_mask:0xf bound_ctrl:1
	v_add_f32_dpp v96, v96, v205 quad_perm:[1,0,3,2] row_mask:0xf bank_mask:0xf bound_ctrl:1
	v_add_f32_dpp v97, v100, v206 quad_perm:[1,0,3,2] row_mask:0xf bank_mask:0xf bound_ctrl:1
	v_add_f32_dpp v22, v22, v207 quad_perm:[1,0,3,2] row_mask:0xf bank_mask:0xf bound_ctrl:1
	v_xor_b32_e32 v200, v83, v23
	v_xor_b32_e32 v201, v83, v97
	v_xor_b32_e32 v202, v83, v96
	v_xor_b32_e32 v203, v83, v22
	v_add_f32_dpp v204, v23, v200 quad_perm:[2,3,0,1] row_mask:0xf bank_mask:0xf bound_ctrl:1
	v_add_f32_dpp v205, v97, v201 quad_perm:[2,3,0,1] row_mask:0xf bank_mask:0xf bound_ctrl:1
	v_add_f32_dpp v206, v96, v202 quad_perm:[2,3,0,1] row_mask:0xf bank_mask:0xf bound_ctrl:1
	v_add_f32_dpp v207, v22, v203 quad_perm:[2,3,0,1] row_mask:0xf bank_mask:0xf bound_ctrl:1
	v_xor_b32_e32 v200, v84, v204
	v_xor_b32_e32 v201, v84, v205
	v_xor_b32_e32 v202, v84, v206
	v_xor_b32_e32 v203, v84, v207
	v_add_f32_dpp v22, v204, v200 row_shl:4 row_mask:0xf bank_mask:0x5
	v_add_f32_dpp v23, v205, v201 row_shl:4 row_mask:0xf bank_mask:0x5
	v_add_f32_dpp v96, v206, v202 row_shl:4 row_mask:0xf bank_mask:0x5
	v_add_f32_dpp v97, v207, v203 row_shl:4 row_mask:0xf bank_mask:0x5
	v_add_f32_dpp v22, v204, v200 row_shr:4 row_mask:0xf bank_mask:0xa
	v_add_f32_dpp v23, v205, v201 row_shr:4 row_mask:0xf bank_mask:0xa
	v_add_f32_dpp v96, v206, v202 row_shr:4 row_mask:0xf bank_mask:0xa
	v_add_f32_dpp v97, v207, v203 row_shr:4 row_mask:0xf bank_mask:0xa
	v_max_f32_e64 v99, |v22|, |v23|
	v_max_f32_e64 v100, |v96|, |v97|
	v_max3_f32 v98, v98, v99, v100
	v_lshlrev_b32_e32 v99, 16, v20
	v_and_b32_e32 v20, 0xffff0000, v20
	v_lshlrev_b32_e32 v100, 16, v21
	v_and_b32_e32 v21, 0xffff0000, v21
	v_add_f32_e32 v101, v99, v20
	v_sub_f32_e32 v20, v99, v20
	v_add_f32_e32 v99, v100, v21
	v_sub_f32_e32 v21, v100, v21
	v_add_f32_e32 v100, v101, v99
	v_sub_f32_e32 v99, v101, v99
	v_add_f32_e32 v102, v20, v21
	v_sub_f32_e32 v20, v20, v21
	v_xor_b32_e32 v204, v82, v100
	v_xor_b32_e32 v205, v82, v99
	v_xor_b32_e32 v206, v82, v102
	v_xor_b32_e32 v207, v82, v20
	v_cvt_pk_bf16_f32 v22, v22, v23
	v_cvt_pk_bf16_f32 v23, v96, v97
	v_add_f32_dpp v21, v100, v204 quad_perm:[1,0,3,2] row_mask:0xf bank_mask:0xf bound_ctrl:1
	v_add_f32_dpp v99, v99, v205 quad_perm:[1,0,3,2] row_mask:0xf bank_mask:0xf bound_ctrl:1
	v_add_f32_dpp v100, v102, v206 quad_perm:[1,0,3,2] row_mask:0xf bank_mask:0xf bound_ctrl:1
	v_add_f32_dpp v20, v20, v207 quad_perm:[1,0,3,2] row_mask:0xf bank_mask:0xf bound_ctrl:1
	v_xor_b32_e32 v200, v83, v21
	v_xor_b32_e32 v201, v83, v100
	v_xor_b32_e32 v202, v83, v99
	v_xor_b32_e32 v203, v83, v20
	v_add_f32_dpp v204, v21, v200 quad_perm:[2,3,0,1] row_mask:0xf bank_mask:0xf bound_ctrl:1
	v_add_f32_dpp v205, v100, v201 quad_perm:[2,3,0,1] row_mask:0xf bank_mask:0xf bound_ctrl:1
	v_add_f32_dpp v206, v99, v202 quad_perm:[2,3,0,1] row_mask:0xf bank_mask:0xf bound_ctrl:1
	v_add_f32_dpp v207, v20, v203 quad_perm:[2,3,0,1] row_mask:0xf bank_mask:0xf bound_ctrl:1
	v_xor_b32_e32 v200, v84, v204
	v_xor_b32_e32 v201, v84, v205
	v_xor_b32_e32 v202, v84, v206
	v_xor_b32_e32 v203, v84, v207
	v_add_f32_dpp v21, v204, v200 row_shl:4 row_mask:0xf bank_mask:0x5
	v_add_f32_dpp v100, v205, v201 row_shl:4 row_mask:0xf bank_mask:0x5
	v_add_f32_dpp v99, v206, v202 row_shl:4 row_mask:0xf bank_mask:0x5
	v_add_f32_dpp v20, v207, v203 row_shl:4 row_mask:0xf bank_mask:0x5
	v_add_f32_dpp v21, v204, v200 row_shr:4 row_mask:0xf bank_mask:0xa
	v_add_f32_dpp v100, v205, v201 row_shr:4 row_mask:0xf bank_mask:0xa
	v_add_f32_dpp v99, v206, v202 row_shr:4 row_mask:0xf bank_mask:0xa
	v_add_f32_dpp v20, v207, v203 row_shr:4 row_mask:0xf bank_mask:0xa
	v_cvt_pk_bf16_f32 v96, v21, v100
	v_max_f32_e64 v101, |v21|, |v100|
	v_max_f32_e64 v102, |v99|, |v20|
	v_max3_f32 v98, v98, v101, v102
	v_lshlrev_b32_e32 v101, 16, v18
	v_and_b32_e32 v18, 0xffff0000, v18
	v_lshlrev_b32_e32 v102, 16, v19
	v_and_b32_e32 v19, 0xffff0000, v19
	v_add_f32_e32 v103, v101, v18
	v_sub_f32_e32 v18, v101, v18
	v_add_f32_e32 v101, v102, v19
	v_sub_f32_e32 v19, v102, v19
	v_add_f32_e32 v102, v103, v101
	v_sub_f32_e32 v101, v103, v101
	v_add_f32_e32 v104, v18, v19
	v_sub_f32_e32 v18, v18, v19
	v_xor_b32_e32 v204, v82, v102
	v_xor_b32_e32 v205, v82, v101
	v_xor_b32_e32 v206, v82, v104
	v_xor_b32_e32 v207, v82, v18
	v_cvt_pk_bf16_f32 v97, v99, v20
	v_add_f32_dpp v19, v102, v204 quad_perm:[1,0,3,2] row_mask:0xf bank_mask:0xf bound_ctrl:1
	v_add_f32_dpp v101, v101, v205 quad_perm:[1,0,3,2] row_mask:0xf bank_mask:0xf bound_ctrl:1
	v_add_f32_dpp v102, v104, v206 quad_perm:[1,0,3,2] row_mask:0xf bank_mask:0xf bound_ctrl:1
	v_add_f32_dpp v18, v18, v207 quad_perm:[1,0,3,2] row_mask:0xf bank_mask:0xf bound_ctrl:1
	v_xor_b32_e32 v200, v83, v19
	v_xor_b32_e32 v201, v83, v102
	v_xor_b32_e32 v202, v83, v101
	v_xor_b32_e32 v203, v83, v18
	v_add_f32_dpp v204, v19, v200 quad_perm:[2,3,0,1] row_mask:0xf bank_mask:0xf bound_ctrl:1
	v_add_f32_dpp v205, v102, v201 quad_perm:[2,3,0,1] row_mask:0xf bank_mask:0xf bound_ctrl:1
	v_add_f32_dpp v206, v101, v202 quad_perm:[2,3,0,1] row_mask:0xf bank_mask:0xf bound_ctrl:1
	v_add_f32_dpp v207, v18, v203 quad_perm:[2,3,0,1] row_mask:0xf bank_mask:0xf bound_ctrl:1
	v_xor_b32_e32 v200, v84, v204
	v_xor_b32_e32 v201, v84, v205
	v_xor_b32_e32 v202, v84, v206
	v_xor_b32_e32 v203, v84, v207
	v_add_f32_dpp v19, v204, v200 row_shl:4 row_mask:0xf bank_mask:0x5
	v_add_f32_dpp v102, v205, v201 row_shl:4 row_mask:0xf bank_mask:0x5
	v_add_f32_dpp v101, v206, v202 row_shl:4 row_mask:0xf bank_mask:0x5
	v_add_f32_dpp v18, v207, v203 row_shl:4 row_mask:0xf bank_mask:0x5
	v_add_f32_dpp v19, v204, v200 row_shr:4 row_mask:0xf bank_mask:0xa
	v_add_f32_dpp v102, v205, v201 row_shr:4 row_mask:0xf bank_mask:0xa
	v_add_f32_dpp v101, v206, v202 row_shr:4 row_mask:0xf bank_mask:0xa
	v_add_f32_dpp v18, v207, v203 row_shr:4 row_mask:0xf bank_mask:0xa
	v_max_f32_e64 v103, |v19|, |v102|
	v_max_f32_e64 v104, |v101|, |v18|
	v_max3_f32 v98, v98, v103, v104
	v_lshlrev_b32_e32 v103, 16, v16
	v_and_b32_e32 v16, 0xffff0000, v16
	v_lshlrev_b32_e32 v104, 16, v17
	v_and_b32_e32 v17, 0xffff0000, v17
	v_add_f32_e32 v105, v103, v16
	v_sub_f32_e32 v16, v103, v16
	v_add_f32_e32 v103, v104, v17
	v_sub_f32_e32 v17, v104, v17
	v_add_f32_e32 v104, v105, v103
	v_sub_f32_e32 v103, v105, v103
	v_add_f32_e32 v106, v16, v17
	v_sub_f32_e32 v16, v16, v17
	v_xor_b32_e32 v204, v82, v104
	v_xor_b32_e32 v205, v82, v103
	v_xor_b32_e32 v206, v82, v106
	v_xor_b32_e32 v207, v82, v16
	v_cvt_pk_bf16_f32 v19, v19, v102
	v_add_f32_dpp v17, v104, v204 quad_perm:[1,0,3,2] row_mask:0xf bank_mask:0xf bound_ctrl:1
	v_add_f32_dpp v103, v103, v205 quad_perm:[1,0,3,2] row_mask:0xf bank_mask:0xf bound_ctrl:1
	v_add_f32_dpp v104, v106, v206 quad_perm:[1,0,3,2] row_mask:0xf bank_mask:0xf bound_ctrl:1
	v_add_f32_dpp v16, v16, v207 quad_perm:[1,0,3,2] row_mask:0xf bank_mask:0xf bound_ctrl:1
	v_xor_b32_e32 v200, v83, v17
	v_xor_b32_e32 v201, v83, v104
	v_xor_b32_e32 v202, v83, v103
	v_xor_b32_e32 v203, v83, v16
	v_add_f32_dpp v204, v17, v200 quad_perm:[2,3,0,1] row_mask:0xf bank_mask:0xf bound_ctrl:1
	v_add_f32_dpp v205, v104, v201 quad_perm:[2,3,0,1] row_mask:0xf bank_mask:0xf bound_ctrl:1
	v_add_f32_dpp v206, v103, v202 quad_perm:[2,3,0,1] row_mask:0xf bank_mask:0xf bound_ctrl:1
	v_add_f32_dpp v207, v16, v203 quad_perm:[2,3,0,1] row_mask:0xf bank_mask:0xf bound_ctrl:1
	v_xor_b32_e32 v200, v84, v204
	v_xor_b32_e32 v201, v84, v205
	v_xor_b32_e32 v202, v84, v206
	v_xor_b32_e32 v203, v84, v207
	v_add_f32_dpp v17, v204, v200 row_shl:4 row_mask:0xf bank_mask:0x5
	v_add_f32_dpp v104, v205, v201 row_shl:4 row_mask:0xf bank_mask:0x5
	v_add_f32_dpp v103, v206, v202 row_shl:4 row_mask:0xf bank_mask:0x5
	v_add_f32_dpp v16, v207, v203 row_shl:4 row_mask:0xf bank_mask:0x5
	v_add_f32_dpp v17, v204, v200 row_shr:4 row_mask:0xf bank_mask:0xa
	v_add_f32_dpp v104, v205, v201 row_shr:4 row_mask:0xf bank_mask:0xa
	v_add_f32_dpp v103, v206, v202 row_shr:4 row_mask:0xf bank_mask:0xa
	v_add_f32_dpp v16, v207, v203 row_shr:4 row_mask:0xf bank_mask:0xa
	v_max_f32_e64 v105, |v17|, |v104|
	v_max_f32_e64 v106, |v103|, |v16|
	v_max3_f32 v98, v98, v105, v106
	v_lshlrev_b32_e32 v105, 16, v14
	v_and_b32_e32 v14, 0xffff0000, v14
	v_lshlrev_b32_e32 v106, 16, v15
	v_and_b32_e32 v15, 0xffff0000, v15
	v_add_f32_e32 v107, v105, v14
	v_sub_f32_e32 v14, v105, v14
	v_add_f32_e32 v105, v106, v15
	v_sub_f32_e32 v15, v106, v15
	v_add_f32_e32 v106, v107, v105
	v_sub_f32_e32 v105, v107, v105
	v_add_f32_e32 v108, v14, v15
	v_sub_f32_e32 v14, v14, v15
	v_xor_b32_e32 v204, v82, v106
	v_xor_b32_e32 v205, v82, v105
	v_xor_b32_e32 v206, v82, v108
	v_xor_b32_e32 v207, v82, v14
	v_add_f32_dpp v15, v106, v204 quad_perm:[1,0,3,2] row_mask:0xf bank_mask:0xf bound_ctrl:1
	v_add_f32_dpp v105, v105, v205 quad_perm:[1,0,3,2] row_mask:0xf bank_mask:0xf bound_ctrl:1
	v_add_f32_dpp v106, v108, v206 quad_perm:[1,0,3,2] row_mask:0xf bank_mask:0xf bound_ctrl:1
	v_add_f32_dpp v14, v14, v207 quad_perm:[1,0,3,2] row_mask:0xf bank_mask:0xf bound_ctrl:1
	v_xor_b32_e32 v200, v83, v15
	v_xor_b32_e32 v201, v83, v106
	v_xor_b32_e32 v202, v83, v105
	v_xor_b32_e32 v203, v83, v14
	v_add_f32_dpp v204, v15, v200 quad_perm:[2,3,0,1] row_mask:0xf bank_mask:0xf bound_ctrl:1
	v_add_f32_dpp v205, v106, v201 quad_perm:[2,3,0,1] row_mask:0xf bank_mask:0xf bound_ctrl:1
	v_add_f32_dpp v206, v105, v202 quad_perm:[2,3,0,1] row_mask:0xf bank_mask:0xf bound_ctrl:1
	v_add_f32_dpp v207, v14, v203 quad_perm:[2,3,0,1] row_mask:0xf bank_mask:0xf bound_ctrl:1
	v_xor_b32_e32 v200, v84, v204
	v_xor_b32_e32 v201, v84, v205
	v_xor_b32_e32 v202, v84, v206
	v_xor_b32_e32 v203, v84, v207
	v_add_f32_dpp v15, v204, v200 row_shl:4 row_mask:0xf bank_mask:0x5
	v_add_f32_dpp v106, v205, v201 row_shl:4 row_mask:0xf bank_mask:0x5
	v_add_f32_dpp v105, v206, v202 row_shl:4 row_mask:0xf bank_mask:0x5
	v_add_f32_dpp v14, v207, v203 row_shl:4 row_mask:0xf bank_mask:0x5
	v_add_f32_dpp v15, v204, v200 row_shr:4 row_mask:0xf bank_mask:0xa
	v_add_f32_dpp v106, v205, v201 row_shr:4 row_mask:0xf bank_mask:0xa
	v_add_f32_dpp v105, v206, v202 row_shr:4 row_mask:0xf bank_mask:0xa
	v_add_f32_dpp v14, v207, v203 row_shr:4 row_mask:0xf bank_mask:0xa
	v_max_f32_e64 v107, |v15|, |v106|
	v_max_f32_e64 v108, |v105|, |v14|
	v_max3_f32 v98, v98, v107, v108
	v_lshlrev_b32_e32 v107, 16, v12
	v_and_b32_e32 v12, 0xffff0000, v12
	v_lshlrev_b32_e32 v108, 16, v13
	v_and_b32_e32 v13, 0xffff0000, v13
	v_add_f32_e32 v109, v107, v12
	v_sub_f32_e32 v12, v107, v12
	v_add_f32_e32 v107, v108, v13
	v_sub_f32_e32 v13, v108, v13
	v_add_f32_e32 v108, v109, v107
	v_sub_f32_e32 v107, v109, v107
	v_add_f32_e32 v110, v12, v13
	v_sub_f32_e32 v12, v12, v13
	v_xor_b32_e32 v204, v82, v108
	v_xor_b32_e32 v205, v82, v107
	v_xor_b32_e32 v206, v82, v110
	v_xor_b32_e32 v207, v82, v12
	v_add_f32_dpp v13, v108, v204 quad_perm:[1,0,3,2] row_mask:0xf bank_mask:0xf bound_ctrl:1
	v_add_f32_dpp v107, v107, v205 quad_perm:[1,0,3,2] row_mask:0xf bank_mask:0xf bound_ctrl:1
	v_add_f32_dpp v108, v110, v206 quad_perm:[1,0,3,2] row_mask:0xf bank_mask:0xf bound_ctrl:1
	v_add_f32_dpp v12, v12, v207 quad_perm:[1,0,3,2] row_mask:0xf bank_mask:0xf bound_ctrl:1
	v_xor_b32_e32 v200, v83, v13
	v_xor_b32_e32 v201, v83, v108
	v_xor_b32_e32 v202, v83, v107
	v_xor_b32_e32 v203, v83, v12
	v_add_f32_dpp v204, v13, v200 quad_perm:[2,3,0,1] row_mask:0xf bank_mask:0xf bound_ctrl:1
	v_add_f32_dpp v205, v108, v201 quad_perm:[2,3,0,1] row_mask:0xf bank_mask:0xf bound_ctrl:1
	v_add_f32_dpp v206, v107, v202 quad_perm:[2,3,0,1] row_mask:0xf bank_mask:0xf bound_ctrl:1
	v_add_f32_dpp v207, v12, v203 quad_perm:[2,3,0,1] row_mask:0xf bank_mask:0xf bound_ctrl:1
	v_xor_b32_e32 v200, v84, v204
	v_xor_b32_e32 v201, v84, v205
	v_xor_b32_e32 v202, v84, v206
	v_xor_b32_e32 v203, v84, v207
	v_add_f32_dpp v13, v204, v200 row_shl:4 row_mask:0xf bank_mask:0x5
	v_add_f32_dpp v108, v205, v201 row_shl:4 row_mask:0xf bank_mask:0x5
	v_add_f32_dpp v107, v206, v202 row_shl:4 row_mask:0xf bank_mask:0x5
	v_add_f32_dpp v12, v207, v203 row_shl:4 row_mask:0xf bank_mask:0x5
	v_add_f32_dpp v13, v204, v200 row_shr:4 row_mask:0xf bank_mask:0xa
	v_add_f32_dpp v108, v205, v201 row_shr:4 row_mask:0xf bank_mask:0xa
	v_add_f32_dpp v107, v206, v202 row_shr:4 row_mask:0xf bank_mask:0xa
	v_add_f32_dpp v12, v207, v203 row_shr:4 row_mask:0xf bank_mask:0xa
	v_max_f32_e64 v109, |v13|, |v108|
	v_max_f32_e64 v110, |v107|, |v12|
	v_max3_f32 v98, v98, v109, v110
	v_lshlrev_b32_e32 v109, 16, v10
	v_and_b32_e32 v10, 0xffff0000, v10
	v_lshlrev_b32_e32 v110, 16, v11
	v_and_b32_e32 v11, 0xffff0000, v11
	v_add_f32_e32 v111, v109, v10
	v_sub_f32_e32 v10, v109, v10
	v_add_f32_e32 v109, v110, v11
	v_sub_f32_e32 v11, v110, v11
	v_add_f32_e32 v110, v111, v109
	v_sub_f32_e32 v109, v111, v109
	v_add_f32_e32 v112, v10, v11
	v_sub_f32_e32 v10, v10, v11
	v_xor_b32_e32 v204, v82, v110
	v_xor_b32_e32 v205, v82, v109
	v_xor_b32_e32 v206, v82, v112
	v_xor_b32_e32 v207, v82, v10
	v_add_f32_dpp v11, v110, v204 quad_perm:[1,0,3,2] row_mask:0xf bank_mask:0xf bound_ctrl:1
	v_add_f32_dpp v109, v109, v205 quad_perm:[1,0,3,2] row_mask:0xf bank_mask:0xf bound_ctrl:1
	v_add_f32_dpp v110, v112, v206 quad_perm:[1,0,3,2] row_mask:0xf bank_mask:0xf bound_ctrl:1
	v_add_f32_dpp v10, v10, v207 quad_perm:[1,0,3,2] row_mask:0xf bank_mask:0xf bound_ctrl:1
	v_xor_b32_e32 v200, v83, v11
	v_xor_b32_e32 v201, v83, v110
	v_xor_b32_e32 v202, v83, v109
	v_xor_b32_e32 v203, v83, v10
	v_add_f32_dpp v204, v11, v200 quad_perm:[2,3,0,1] row_mask:0xf bank_mask:0xf bound_ctrl:1
	v_add_f32_dpp v205, v110, v201 quad_perm:[2,3,0,1] row_mask:0xf bank_mask:0xf bound_ctrl:1
	v_add_f32_dpp v206, v109, v202 quad_perm:[2,3,0,1] row_mask:0xf bank_mask:0xf bound_ctrl:1
	v_add_f32_dpp v207, v10, v203 quad_perm:[2,3,0,1] row_mask:0xf bank_mask:0xf bound_ctrl:1
	v_xor_b32_e32 v200, v84, v204
	v_xor_b32_e32 v201, v84, v205
	v_xor_b32_e32 v202, v84, v206
	v_xor_b32_e32 v203, v84, v207
	v_add_f32_dpp v11, v204, v200 row_shl:4 row_mask:0xf bank_mask:0x5
	v_add_f32_dpp v110, v205, v201 row_shl:4 row_mask:0xf bank_mask:0x5
	v_add_f32_dpp v109, v206, v202 row_shl:4 row_mask:0xf bank_mask:0x5
	v_add_f32_dpp v10, v207, v203 row_shl:4 row_mask:0xf bank_mask:0x5
	v_add_f32_dpp v11, v204, v200 row_shr:4 row_mask:0xf bank_mask:0xa
	v_add_f32_dpp v110, v205, v201 row_shr:4 row_mask:0xf bank_mask:0xa
	v_add_f32_dpp v109, v206, v202 row_shr:4 row_mask:0xf bank_mask:0xa
	v_add_f32_dpp v10, v207, v203 row_shr:4 row_mask:0xf bank_mask:0xa
	v_max_f32_e64 v111, |v11|, |v110|
	v_max_f32_e64 v112, |v109|, |v10|
	v_max3_f32 v98, v98, v111, v112
	v_lshlrev_b32_e32 v111, 16, v8
	v_and_b32_e32 v8, 0xffff0000, v8
	v_lshlrev_b32_e32 v112, 16, v9
	v_and_b32_e32 v9, 0xffff0000, v9
	v_add_f32_e32 v113, v111, v8
	v_sub_f32_e32 v8, v111, v8
	v_add_f32_e32 v111, v112, v9
	v_sub_f32_e32 v9, v112, v9
	v_add_f32_e32 v112, v113, v111
	v_sub_f32_e32 v111, v113, v111
	v_add_f32_e32 v114, v8, v9
	v_sub_f32_e32 v8, v8, v9
	v_xor_b32_e32 v204, v82, v112
	v_xor_b32_e32 v205, v82, v111
	v_xor_b32_e32 v206, v82, v114
	v_xor_b32_e32 v207, v82, v8
	v_add_f32_dpp v9, v112, v204 quad_perm:[1,0,3,2] row_mask:0xf bank_mask:0xf bound_ctrl:1
	v_add_f32_dpp v111, v111, v205 quad_perm:[1,0,3,2] row_mask:0xf bank_mask:0xf bound_ctrl:1
	v_add_f32_dpp v112, v114, v206 quad_perm:[1,0,3,2] row_mask:0xf bank_mask:0xf bound_ctrl:1
	v_add_f32_dpp v8, v8, v207 quad_perm:[1,0,3,2] row_mask:0xf bank_mask:0xf bound_ctrl:1
	v_xor_b32_e32 v200, v83, v9
	v_xor_b32_e32 v201, v83, v112
	v_xor_b32_e32 v202, v83, v111
	v_xor_b32_e32 v203, v83, v8
	v_add_f32_dpp v204, v9, v200 quad_perm:[2,3,0,1] row_mask:0xf bank_mask:0xf bound_ctrl:1
	v_add_f32_dpp v205, v112, v201 quad_perm:[2,3,0,1] row_mask:0xf bank_mask:0xf bound_ctrl:1
	v_add_f32_dpp v206, v111, v202 quad_perm:[2,3,0,1] row_mask:0xf bank_mask:0xf bound_ctrl:1
	v_add_f32_dpp v207, v8, v203 quad_perm:[2,3,0,1] row_mask:0xf bank_mask:0xf bound_ctrl:1
	v_xor_b32_e32 v200, v84, v204
	v_xor_b32_e32 v201, v84, v205
	v_xor_b32_e32 v202, v84, v206
	v_xor_b32_e32 v203, v84, v207
	v_add_f32_dpp v9, v204, v200 row_shl:4 row_mask:0xf bank_mask:0x5
	v_add_f32_dpp v112, v205, v201 row_shl:4 row_mask:0xf bank_mask:0x5
	v_add_f32_dpp v111, v206, v202 row_shl:4 row_mask:0xf bank_mask:0x5
	v_add_f32_dpp v8, v207, v203 row_shl:4 row_mask:0xf bank_mask:0x5
	v_add_f32_dpp v9, v204, v200 row_shr:4 row_mask:0xf bank_mask:0xa
	v_add_f32_dpp v112, v205, v201 row_shr:4 row_mask:0xf bank_mask:0xa
	v_add_f32_dpp v111, v206, v202 row_shr:4 row_mask:0xf bank_mask:0xa
	v_add_f32_dpp v8, v207, v203 row_shr:4 row_mask:0xf bank_mask:0xa
	v_max_f32_e64 v113, |v9|, |v112|
	v_max_f32_e64 v114, |v111|, |v8|
	v_max3_f32 v98, v98, v113, v114
	v_lshlrev_b32_e32 v113, 16, v6
	v_and_b32_e32 v6, 0xffff0000, v6
	v_lshlrev_b32_e32 v114, 16, v7
	v_and_b32_e32 v7, 0xffff0000, v7
	v_add_f32_e32 v115, v113, v6
	v_sub_f32_e32 v6, v113, v6
	v_add_f32_e32 v113, v114, v7
	v_sub_f32_e32 v7, v114, v7
	v_add_f32_e32 v114, v115, v113
	v_sub_f32_e32 v113, v115, v113
	v_add_f32_e32 v116, v6, v7
	v_sub_f32_e32 v6, v6, v7
	v_xor_b32_e32 v204, v82, v114
	v_xor_b32_e32 v205, v82, v113
	v_xor_b32_e32 v206, v82, v116
	v_xor_b32_e32 v207, v82, v6
	v_add_f32_dpp v7, v114, v204 quad_perm:[1,0,3,2] row_mask:0xf bank_mask:0xf bound_ctrl:1
	v_add_f32_dpp v113, v113, v205 quad_perm:[1,0,3,2] row_mask:0xf bank_mask:0xf bound_ctrl:1
	v_add_f32_dpp v114, v116, v206 quad_perm:[1,0,3,2] row_mask:0xf bank_mask:0xf bound_ctrl:1
	v_add_f32_dpp v6, v6, v207 quad_perm:[1,0,3,2] row_mask:0xf bank_mask:0xf bound_ctrl:1
	v_xor_b32_e32 v200, v83, v7
	v_xor_b32_e32 v201, v83, v114
	v_xor_b32_e32 v202, v83, v113
	v_xor_b32_e32 v203, v83, v6
	v_add_f32_dpp v204, v7, v200 quad_perm:[2,3,0,1] row_mask:0xf bank_mask:0xf bound_ctrl:1
	v_add_f32_dpp v205, v114, v201 quad_perm:[2,3,0,1] row_mask:0xf bank_mask:0xf bound_ctrl:1
	v_add_f32_dpp v206, v113, v202 quad_perm:[2,3,0,1] row_mask:0xf bank_mask:0xf bound_ctrl:1
	v_add_f32_dpp v207, v6, v203 quad_perm:[2,3,0,1] row_mask:0xf bank_mask:0xf bound_ctrl:1
	v_xor_b32_e32 v200, v84, v204
	v_xor_b32_e32 v201, v84, v205
	v_xor_b32_e32 v202, v84, v206
	v_xor_b32_e32 v203, v84, v207
	v_add_f32_dpp v7, v204, v200 row_shl:4 row_mask:0xf bank_mask:0x5
	v_add_f32_dpp v114, v205, v201 row_shl:4 row_mask:0xf bank_mask:0x5
	v_add_f32_dpp v113, v206, v202 row_shl:4 row_mask:0xf bank_mask:0x5
	v_add_f32_dpp v6, v207, v203 row_shl:4 row_mask:0xf bank_mask:0x5
	v_add_f32_dpp v7, v204, v200 row_shr:4 row_mask:0xf bank_mask:0xa
	v_add_f32_dpp v114, v205, v201 row_shr:4 row_mask:0xf bank_mask:0xa
	v_add_f32_dpp v113, v206, v202 row_shr:4 row_mask:0xf bank_mask:0xa
	v_add_f32_dpp v6, v207, v203 row_shr:4 row_mask:0xf bank_mask:0xa
	v_max_f32_e64 v115, |v7|, |v114|
	v_max_f32_e64 v116, |v113|, |v6|
	v_max3_f32 v98, v98, v115, v116
	s_waitcnt vmcnt(0)
	v_lshlrev_b32_e32 v115, 16, v4
	v_and_b32_e32 v4, 0xffff0000, v4
	v_lshlrev_b32_e32 v116, 16, v5
	v_and_b32_e32 v5, 0xffff0000, v5
	v_add_f32_e32 v117, v115, v4
	v_sub_f32_e32 v4, v115, v4
	v_add_f32_e32 v115, v116, v5
	v_sub_f32_e32 v5, v116, v5
	v_add_f32_e32 v116, v117, v115
	v_sub_f32_e32 v115, v117, v115
	v_add_f32_e32 v118, v4, v5
	v_sub_f32_e32 v4, v4, v5
	v_xor_b32_e32 v204, v82, v116
	v_xor_b32_e32 v205, v82, v115
	v_xor_b32_e32 v206, v82, v118
	v_xor_b32_e32 v207, v82, v4
	v_add_f32_dpp v5, v116, v204 quad_perm:[1,0,3,2] row_mask:0xf bank_mask:0xf bound_ctrl:1
	v_add_f32_dpp v115, v115, v205 quad_perm:[1,0,3,2] row_mask:0xf bank_mask:0xf bound_ctrl:1
	v_add_f32_dpp v116, v118, v206 quad_perm:[1,0,3,2] row_mask:0xf bank_mask:0xf bound_ctrl:1
	v_add_f32_dpp v4, v4, v207 quad_perm:[1,0,3,2] row_mask:0xf bank_mask:0xf bound_ctrl:1
	v_xor_b32_e32 v200, v83, v5
	v_xor_b32_e32 v201, v83, v116
	v_xor_b32_e32 v202, v83, v115
	v_xor_b32_e32 v203, v83, v4
	v_add_f32_dpp v204, v5, v200 quad_perm:[2,3,0,1] row_mask:0xf bank_mask:0xf bound_ctrl:1
	v_add_f32_dpp v205, v116, v201 quad_perm:[2,3,0,1] row_mask:0xf bank_mask:0xf bound_ctrl:1
	v_add_f32_dpp v206, v115, v202 quad_perm:[2,3,0,1] row_mask:0xf bank_mask:0xf bound_ctrl:1
	v_add_f32_dpp v207, v4, v203 quad_perm:[2,3,0,1] row_mask:0xf bank_mask:0xf bound_ctrl:1
	v_xor_b32_e32 v200, v84, v204
	v_xor_b32_e32 v201, v84, v205
	v_xor_b32_e32 v202, v84, v206
	v_xor_b32_e32 v203, v84, v207
	v_add_f32_dpp v5, v204, v200 row_shl:4 row_mask:0xf bank_mask:0x5
	v_add_f32_dpp v116, v205, v201 row_shl:4 row_mask:0xf bank_mask:0x5
	v_add_f32_dpp v115, v206, v202 row_shl:4 row_mask:0xf bank_mask:0x5
	v_add_f32_dpp v4, v207, v203 row_shl:4 row_mask:0xf bank_mask:0x5
	v_add_f32_dpp v5, v204, v200 row_shr:4 row_mask:0xf bank_mask:0xa
	v_add_f32_dpp v116, v205, v201 row_shr:4 row_mask:0xf bank_mask:0xa
	v_add_f32_dpp v115, v206, v202 row_shr:4 row_mask:0xf bank_mask:0xa
	v_add_f32_dpp v4, v207, v203 row_shr:4 row_mask:0xf bank_mask:0xa
	v_max_f32_e64 v117, |v5|, |v116|
	v_max_f32_e64 v118, |v115|, |v4|
	v_max3_f32 v98, v98, v117, v118
	ds_swizzle_b32 v117, v98 offset:swizzle(SWAP,1)
	s_waitcnt lgkmcnt(0)
	v_max_f32_e32 v94, v117, v117
	v_max_f32_e32 v94, v98, v94
	ds_swizzle_b32 v95, v94 offset:swizzle(SWAP,2)
	v_cvt_pk_bf16_f32 v98, v101, v18
	s_waitcnt lgkmcnt(0)
	v_max_f32_e32 v18, v95, v95
	v_max_f32_e32 v18, v94, v18
	ds_swizzle_b32 v20, v18 offset:swizzle(SWAP,4)
	v_cvt_pk_bf16_f32 v94, v17, v104
	v_cvt_pk_bf16_f32 v95, v103, v16
	v_cvt_pk_bf16_f32 v99, v15, v106
	v_cvt_pk_bf16_f32 v100, v105, v14
	s_waitcnt lgkmcnt(0)
	v_max_f32_e32 v14, v20, v20
	v_max_f32_e32 v14, v18, v14
	ds_swizzle_b32 v16, v14 offset:swizzle(SWAP,8)
	v_cvt_pk_bf16_f32 v18, v13, v108
	v_cvt_pk_bf16_f32 v101, v107, v12
	v_cvt_pk_bf16_f32 v15, v11, v110
	v_cvt_pk_bf16_f32 v17, v109, v10
	s_waitcnt lgkmcnt(0)
	v_max_f32_e32 v10, v16, v16
	v_max_f32_e32 v10, v14, v10
	ds_swizzle_b32 v12, v10 offset:swizzle(SWAP,16)
	v_cvt_pk_bf16_f32 v13, v9, v112
	v_cvt_pk_bf16_f32 v14, v111, v8
	v_cvt_pk_bf16_f32 v9, v7, v114
	v_cvt_pk_bf16_f32 v11, v113, v6
	s_waitcnt lgkmcnt(0)
	v_max_f32_e32 v6, v12, v12
	v_max_f32_e32 v6, v10, v6
	v_mov_b32_e32 v7, v6
	s_nop 1
	v_permlane32_swap_b32_e32 v6, v7
	v_max_f32_e32 v7, v7, v7
	v_max_f32_e32 v6, v6, v6
	v_max_f32_e32 v6, v6, v7
	v_mul_f32_e32 v8, 0x3f808000, v6
	v_div_scale_f32 v6, s[18:19], v8, v8, s27
	v_rcp_f32_e32 v7, v6
	v_cvt_pk_bf16_f32 v10, v5, v116
	v_cvt_pk_bf16_f32 v12, v115, v4
	v_lshl_add_u64 v[4:5], s[8:9], 0, v[0:1]
	v_fma_f32 v16, -v6, v7, 1.0
	v_fmac_f32_e32 v7, v16, v7
	v_div_scale_f32 v16, vcc, s27, v8, s27
	v_mul_f32_e32 v20, v16, v7
	v_fma_f32 v21, -v6, v20, v16
	v_fmac_f32_e32 v20, v21, v7
	v_fma_f32 v6, -v6, v20, v16
	v_div_fmas_f32 v6, v6, v7, v20
	v_div_fixup_f32 v6, v6, v8, s27
	v_cmp_lt_f32_e32 vcc, 0, v8
	v_lshlrev_b32_e32 v7, 16, v87
	v_lshlrev_b32_e32 v20, 16, v86
	v_cndmask_b32_e32 v16, 0, v6, vcc
	v_and_b32_e32 v6, 0xffff0000, v87
	v_fmaak_f32 v6, v6, v16, 0x4b400000
	v_fmaak_f32 v7, v7, v16, 0x4b400000
	v_perm_b32 v6, v6, v7, s28
	v_and_b32_e32 v7, 0xffff0000, v86
	v_fmaak_f32 v7, v7, v16, 0x4b400000
	v_fmaak_f32 v20, v20, v16, 0x4b400000
	v_perm_b32 v7, v7, v20, s28
	v_add_co_u32_e32 v20, vcc, s30, v4
	v_perm_b32 v86, v6, v7, s29
	s_nop 0
	v_addc_co_u32_e32 v21, vcc, 0, v5, vcc
	v_add_co_u32_e32 v6, vcc, s31, v4
	v_lshlrev_b32_e32 v87, 16, v89
	s_nop 0
	v_addc_co_u32_e32 v7, vcc, 0, v5, vcc
	global_store_dword v[6:7], v86, off offset:-4096 nt
	v_and_b32_e32 v86, 0xffff0000, v89
	v_fmaak_f32 v86, v86, v16, 0x4b400000
	v_fmaak_f32 v87, v87, v16, 0x4b400000
	v_perm_b32 v86, v86, v87, s28
	v_and_b32_e32 v87, 0xffff0000, v88
	v_lshlrev_b32_e32 v88, 16, v88
	v_fmaak_f32 v87, v87, v16, 0x4b400000
	v_fmaak_f32 v88, v88, v16, 0x4b400000
	v_perm_b32 v87, v87, v88, s28
	v_perm_b32 v86, v86, v87, s29
	global_store_dword v[20:21], v86, off offset:256 nt
	v_and_b32_e32 v86, 0xffff0000, v91
	v_lshlrev_b32_e32 v87, 16, v91
	v_fmaak_f32 v86, v86, v16, 0x4b400000
	v_fmaak_f32 v87, v87, v16, 0x4b400000
	v_perm_b32 v86, v86, v87, s28
	v_and_b32_e32 v87, 0xffff0000, v90
	v_lshlrev_b32_e32 v88, 16, v90
	v_fmaak_f32 v87, v87, v16, 0x4b400000
	v_fmaak_f32 v88, v88, v16, 0x4b400000
	v_perm_b32 v87, v87, v88, s28
	v_perm_b32 v86, v86, v87, s29
	global_store_dword v[20:21], v86, off offset:512 nt
	v_and_b32_e32 v86, 0xffff0000, v93
	v_lshlrev_b32_e32 v87, 16, v93
	v_fmaak_f32 v86, v86, v16, 0x4b400000
	v_fmaak_f32 v87, v87, v16, 0x4b400000
	v_perm_b32 v86, v86, v87, s28
	v_and_b32_e32 v87, 0xffff0000, v92
	v_lshlrev_b32_e32 v88, 16, v92
	v_fmaak_f32 v87, v87, v16, 0x4b400000
	v_fmaak_f32 v88, v88, v16, 0x4b400000
	v_perm_b32 v87, v87, v88, s28
	v_perm_b32 v86, v86, v87, s29
	global_store_dword v[20:21], v86, off offset:768 nt
	v_and_b32_e32 v86, 0xffff0000, v81
	v_lshlrev_b32_e32 v81, 16, v81
	v_fmaak_f32 v86, v86, v16, 0x4b400000
	v_fmaak_f32 v81, v81, v16, 0x4b400000
	v_perm_b32 v81, v86, v81, s28
	v_and_b32_e32 v86, 0xffff0000, v80
	v_lshlrev_b32_e32 v80, 16, v80
	v_fmaak_f32 v86, v86, v16, 0x4b400000
	v_fmaak_f32 v80, v80, v16, 0x4b400000
	v_perm_b32 v80, v86, v80, s28
	v_perm_b32 v80, v81, v80, s29
	global_store_dword v[20:21], v80, off offset:1024 nt
	v_and_b32_e32 v80, 0xffff0000, v79
	v_lshlrev_b32_e32 v79, 16, v79
	v_fmaak_f32 v80, v80, v16, 0x4b400000
	v_fmaak_f32 v79, v79, v16, 0x4b400000
	v_perm_b32 v79, v80, v79, s28
	v_and_b32_e32 v80, 0xffff0000, v78
	v_lshlrev_b32_e32 v78, 16, v78
	v_fmaak_f32 v80, v80, v16, 0x4b400000
	v_fmaak_f32 v78, v78, v16, 0x4b400000
	v_perm_b32 v78, v80, v78, s28
	v_perm_b32 v78, v79, v78, s29
	global_store_dword v[20:21], v78, off offset:1280 nt
	v_and_b32_e32 v78, 0xffff0000, v77
	v_lshlrev_b32_e32 v77, 16, v77
	v_fmaak_f32 v78, v78, v16, 0x4b400000
	v_fmaak_f32 v77, v77, v16, 0x4b400000
	v_perm_b32 v77, v78, v77, s28
	v_and_b32_e32 v78, 0xffff0000, v76
	v_lshlrev_b32_e32 v76, 16, v76
	v_fmaak_f32 v78, v78, v16, 0x4b400000
	v_fmaak_f32 v76, v76, v16, 0x4b400000
	v_perm_b32 v76, v78, v76, s28
	v_perm_b32 v76, v77, v76, s29
	global_store_dword v[20:21], v76, off offset:1536 nt
	v_and_b32_e32 v76, 0xffff0000, v75
	v_lshlrev_b32_e32 v75, 16, v75
	v_fmaak_f32 v76, v76, v16, 0x4b400000
	v_fmaak_f32 v75, v75, v16, 0x4b400000
	v_perm_b32 v75, v76, v75, s28
	v_and_b32_e32 v76, 0xffff0000, v74
	v_lshlrev_b32_e32 v74, 16, v74
	v_fmaak_f32 v76, v76, v16, 0x4b400000
	v_fmaak_f32 v74, v74, v16, 0x4b400000
	v_perm_b32 v74, v76, v74, s28
	v_perm_b32 v74, v75, v74, s29
	global_store_dword v[20:21], v74, off offset:1792 nt
	v_and_b32_e32 v74, 0xffff0000, v73
	v_lshlrev_b32_e32 v73, 16, v73
	v_fmaak_f32 v74, v74, v16, 0x4b400000
	v_fmaak_f32 v73, v73, v16, 0x4b400000
	v_perm_b32 v73, v74, v73, s28
	v_and_b32_e32 v74, 0xffff0000, v72
	v_lshlrev_b32_e32 v72, 16, v72
	v_fmaak_f32 v74, v74, v16, 0x4b400000
	v_fmaak_f32 v72, v72, v16, 0x4b400000
	v_perm_b32 v72, v74, v72, s28
	v_perm_b32 v72, v73, v72, s29
	global_store_dword v[20:21], v72, off offset:2048 nt
	v_and_b32_e32 v72, 0xffff0000, v71
	v_lshlrev_b32_e32 v71, 16, v71
	v_fmaak_f32 v72, v72, v16, 0x4b400000
	v_fmaak_f32 v71, v71, v16, 0x4b400000
	v_perm_b32 v71, v72, v71, s28
	v_and_b32_e32 v72, 0xffff0000, v70
	v_lshlrev_b32_e32 v70, 16, v70
	v_fmaak_f32 v72, v72, v16, 0x4b400000
	v_fmaak_f32 v70, v70, v16, 0x4b400000
	v_perm_b32 v70, v72, v70, s28
	v_perm_b32 v70, v71, v70, s29
	global_store_dword v[20:21], v70, off offset:2304 nt
	v_and_b32_e32 v70, 0xffff0000, v69
	v_lshlrev_b32_e32 v69, 16, v69
	v_fmaak_f32 v70, v70, v16, 0x4b400000
	v_fmaak_f32 v69, v69, v16, 0x4b400000
	v_perm_b32 v69, v70, v69, s28
	v_and_b32_e32 v70, 0xffff0000, v68
	v_lshlrev_b32_e32 v68, 16, v68
	v_fmaak_f32 v70, v70, v16, 0x4b400000
	v_fmaak_f32 v68, v68, v16, 0x4b400000
	v_perm_b32 v68, v70, v68, s28
	v_perm_b32 v68, v69, v68, s29
	global_store_dword v[20:21], v68, off offset:2560 nt
	v_and_b32_e32 v68, 0xffff0000, v67
	v_lshlrev_b32_e32 v67, 16, v67
	v_fmaak_f32 v68, v68, v16, 0x4b400000
	v_fmaak_f32 v67, v67, v16, 0x4b400000
	v_perm_b32 v67, v68, v67, s28
	v_and_b32_e32 v68, 0xffff0000, v66
	v_lshlrev_b32_e32 v66, 16, v66
	v_fmaak_f32 v68, v68, v16, 0x4b400000
	v_fmaak_f32 v66, v66, v16, 0x4b400000
	v_perm_b32 v66, v68, v66, s28
	v_perm_b32 v66, v67, v66, s29
	global_store_dword v[20:21], v66, off offset:2816 nt
	v_and_b32_e32 v66, 0xffff0000, v65
	v_lshlrev_b32_e32 v65, 16, v65
	v_fmaak_f32 v66, v66, v16, 0x4b400000
	v_fmaak_f32 v65, v65, v16, 0x4b400000
	v_perm_b32 v65, v66, v65, s28
	v_and_b32_e32 v66, 0xffff0000, v64
	v_lshlrev_b32_e32 v64, 16, v64
	v_fmaak_f32 v66, v66, v16, 0x4b400000
	v_fmaak_f32 v64, v64, v16, 0x4b400000
	v_perm_b32 v64, v66, v64, s28
	v_perm_b32 v64, v65, v64, s29
	global_store_dword v[20:21], v64, off offset:3072 nt
	v_and_b32_e32 v64, 0xffff0000, v63
	v_lshlrev_b32_e32 v63, 16, v63
	v_fmaak_f32 v64, v64, v16, 0x4b400000
	v_fmaak_f32 v63, v63, v16, 0x4b400000
	v_perm_b32 v63, v64, v63, s28
	v_and_b32_e32 v64, 0xffff0000, v62
	v_lshlrev_b32_e32 v62, 16, v62
	v_fmaak_f32 v64, v64, v16, 0x4b400000
	v_fmaak_f32 v62, v62, v16, 0x4b400000
	v_perm_b32 v62, v64, v62, s28
	v_perm_b32 v62, v63, v62, s29
	global_store_dword v[20:21], v62, off offset:3328 nt
	v_and_b32_e32 v62, 0xffff0000, v61
	v_lshlrev_b32_e32 v61, 16, v61
	v_fmaak_f32 v62, v62, v16, 0x4b400000
	v_fmaak_f32 v61, v61, v16, 0x4b400000
	v_perm_b32 v61, v62, v61, s28
	v_and_b32_e32 v62, 0xffff0000, v60
	v_lshlrev_b32_e32 v60, 16, v60
	v_fmaak_f32 v62, v62, v16, 0x4b400000
	v_fmaak_f32 v60, v60, v16, 0x4b400000
	v_perm_b32 v60, v62, v60, s28
	v_perm_b32 v60, v61, v60, s29
	global_store_dword v[20:21], v60, off offset:3584 nt
	v_and_b32_e32 v60, 0xffff0000, v59
	v_lshlrev_b32_e32 v59, 16, v59
	v_fmaak_f32 v60, v60, v16, 0x4b400000
	v_fmaak_f32 v59, v59, v16, 0x4b400000
	v_perm_b32 v59, v60, v59, s28
	v_and_b32_e32 v60, 0xffff0000, v58
	v_lshlrev_b32_e32 v58, 16, v58
	v_fmaak_f32 v60, v60, v16, 0x4b400000
	v_fmaak_f32 v58, v58, v16, 0x4b400000
	v_perm_b32 v58, v60, v58, s28
	v_perm_b32 v58, v59, v58, s29
	global_store_dword v[20:21], v58, off offset:3840 nt
	v_and_b32_e32 v20, 0xffff0000, v57
	v_lshlrev_b32_e32 v21, 16, v57
	v_fmaak_f32 v20, v20, v16, 0x4b400000
	v_fmaak_f32 v21, v21, v16, 0x4b400000
	v_perm_b32 v20, v20, v21, s28
	v_and_b32_e32 v21, 0xffff0000, v56
	v_lshlrev_b32_e32 v56, 16, v56
	v_fmaak_f32 v21, v21, v16, 0x4b400000
	v_fmaak_f32 v56, v56, v16, 0x4b400000
	v_perm_b32 v21, v21, v56, s28
	v_perm_b32 v20, v20, v21, s29
	global_store_dword v[6:7], v20, off nt
	v_and_b32_e32 v20, 0xffff0000, v55
	v_lshlrev_b32_e32 v21, 16, v55
	v_fmaak_f32 v20, v20, v16, 0x4b400000
	v_fmaak_f32 v21, v21, v16, 0x4b400000
	v_perm_b32 v20, v20, v21, s28
	v_and_b32_e32 v21, 0xffff0000, v54
	v_lshlrev_b32_e32 v54, 16, v54
	v_fmaak_f32 v21, v21, v16, 0x4b400000
	v_fmaak_f32 v54, v54, v16, 0x4b400000
	v_perm_b32 v21, v21, v54, s28
	v_perm_b32 v20, v20, v21, s29
	global_store_dword v[6:7], v20, off offset:256 nt
	v_and_b32_e32 v20, 0xffff0000, v53
	v_lshlrev_b32_e32 v21, 16, v53
	v_fmaak_f32 v20, v20, v16, 0x4b400000
	v_fmaak_f32 v21, v21, v16, 0x4b400000
	v_perm_b32 v20, v20, v21, s28
	v_and_b32_e32 v21, 0xffff0000, v52
	v_lshlrev_b32_e32 v52, 16, v52
	v_fmaak_f32 v21, v21, v16, 0x4b400000
	v_fmaak_f32 v52, v52, v16, 0x4b400000
	v_perm_b32 v21, v21, v52, s28
	v_perm_b32 v20, v20, v21, s29
	global_store_dword v[6:7], v20, off offset:512 nt
	v_and_b32_e32 v20, 0xffff0000, v51
	v_lshlrev_b32_e32 v21, 16, v51
	v_fmaak_f32 v20, v20, v16, 0x4b400000
	v_fmaak_f32 v21, v21, v16, 0x4b400000
	v_perm_b32 v20, v20, v21, s28
	v_and_b32_e32 v21, 0xffff0000, v50
	v_lshlrev_b32_e32 v50, 16, v50
	v_fmaak_f32 v21, v21, v16, 0x4b400000
	v_fmaak_f32 v50, v50, v16, 0x4b400000
	v_perm_b32 v21, v21, v50, s28
	v_perm_b32 v20, v20, v21, s29
	global_store_dword v[6:7], v20, off offset:768 nt
	v_and_b32_e32 v20, 0xffff0000, v49
	v_lshlrev_b32_e32 v21, 16, v49
	v_fmaak_f32 v20, v20, v16, 0x4b400000
	v_fmaak_f32 v21, v21, v16, 0x4b400000
	v_perm_b32 v20, v20, v21, s28
	v_and_b32_e32 v21, 0xffff0000, v48
	v_lshlrev_b32_e32 v48, 16, v48
	v_fmaak_f32 v21, v21, v16, 0x4b400000
	v_fmaak_f32 v48, v48, v16, 0x4b400000
	v_perm_b32 v21, v21, v48, s28
	v_perm_b32 v20, v20, v21, s29
	global_store_dword v[6:7], v20, off offset:1024 nt
	v_and_b32_e32 v20, 0xffff0000, v47
	v_lshlrev_b32_e32 v21, 16, v47
	v_fmaak_f32 v20, v20, v16, 0x4b400000
	v_fmaak_f32 v21, v21, v16, 0x4b400000
	v_perm_b32 v20, v20, v21, s28
	v_and_b32_e32 v21, 0xffff0000, v46
	v_lshlrev_b32_e32 v46, 16, v46
	v_fmaak_f32 v21, v21, v16, 0x4b400000
	v_fmaak_f32 v46, v46, v16, 0x4b400000
	v_perm_b32 v21, v21, v46, s28
	v_perm_b32 v20, v20, v21, s29
	global_store_dword v[6:7], v20, off offset:1280 nt
	v_and_b32_e32 v20, 0xffff0000, v45
	v_lshlrev_b32_e32 v21, 16, v45
	v_fmaak_f32 v20, v20, v16, 0x4b400000
	v_fmaak_f32 v21, v21, v16, 0x4b400000
	v_perm_b32 v20, v20, v21, s28
	v_and_b32_e32 v21, 0xffff0000, v44
	v_lshlrev_b32_e32 v44, 16, v44
	v_fmaak_f32 v21, v21, v16, 0x4b400000
	v_fmaak_f32 v44, v44, v16, 0x4b400000
	v_perm_b32 v21, v21, v44, s28
	v_perm_b32 v20, v20, v21, s29
	global_store_dword v[6:7], v20, off offset:1536 nt
	v_and_b32_e32 v20, 0xffff0000, v43
	v_lshlrev_b32_e32 v21, 16, v43
	v_fmaak_f32 v20, v20, v16, 0x4b400000
	v_fmaak_f32 v21, v21, v16, 0x4b400000
	v_perm_b32 v20, v20, v21, s28
	v_and_b32_e32 v21, 0xffff0000, v42
	v_lshlrev_b32_e32 v42, 16, v42
	v_fmaak_f32 v21, v21, v16, 0x4b400000
	v_fmaak_f32 v42, v42, v16, 0x4b400000
	v_perm_b32 v21, v21, v42, s28
	v_perm_b32 v20, v20, v21, s29
	global_store_dword v[6:7], v20, off offset:1792 nt
	v_and_b32_e32 v20, 0xffff0000, v41
	v_lshlrev_b32_e32 v21, 16, v41
	v_fmaak_f32 v20, v20, v16, 0x4b400000
	v_fmaak_f32 v21, v21, v16, 0x4b400000
	v_perm_b32 v20, v20, v21, s28
	v_and_b32_e32 v21, 0xffff0000, v40
	v_lshlrev_b32_e32 v40, 16, v40
	v_fmaak_f32 v21, v21, v16, 0x4b400000
	v_fmaak_f32 v40, v40, v16, 0x4b400000
	v_perm_b32 v21, v21, v40, s28
	v_perm_b32 v20, v20, v21, s29
	global_store_dword v[6:7], v20, off offset:2048 nt
	v_and_b32_e32 v20, 0xffff0000, v39
	v_lshlrev_b32_e32 v21, 16, v39
	v_fmaak_f32 v20, v20, v16, 0x4b400000
	v_fmaak_f32 v21, v21, v16, 0x4b400000
	v_perm_b32 v20, v20, v21, s28
	v_and_b32_e32 v21, 0xffff0000, v38
	v_lshlrev_b32_e32 v38, 16, v38
	v_fmaak_f32 v21, v21, v16, 0x4b400000
	v_fmaak_f32 v38, v38, v16, 0x4b400000
	v_perm_b32 v21, v21, v38, s28
	v_perm_b32 v20, v20, v21, s29
	global_store_dword v[6:7], v20, off offset:2304 nt
	v_and_b32_e32 v20, 0xffff0000, v37
	v_lshlrev_b32_e32 v21, 16, v37
	v_fmaak_f32 v20, v20, v16, 0x4b400000
	v_fmaak_f32 v21, v21, v16, 0x4b400000
	v_perm_b32 v20, v20, v21, s28
	v_and_b32_e32 v21, 0xffff0000, v36
	v_lshlrev_b32_e32 v36, 16, v36
	v_fmaak_f32 v21, v21, v16, 0x4b400000
	v_fmaak_f32 v36, v36, v16, 0x4b400000
	v_perm_b32 v21, v21, v36, s28
	v_perm_b32 v20, v20, v21, s29
	global_store_dword v[6:7], v20, off offset:2560 nt
	v_and_b32_e32 v20, 0xffff0000, v35
	v_lshlrev_b32_e32 v21, 16, v35
	v_fmaak_f32 v20, v20, v16, 0x4b400000
	v_fmaak_f32 v21, v21, v16, 0x4b400000
	v_perm_b32 v20, v20, v21, s28
	v_and_b32_e32 v21, 0xffff0000, v34
	v_lshlrev_b32_e32 v34, 16, v34
	v_fmaak_f32 v21, v21, v16, 0x4b400000
	v_fmaak_f32 v34, v34, v16, 0x4b400000
	v_perm_b32 v21, v21, v34, s28
	v_perm_b32 v20, v20, v21, s29
	global_store_dword v[6:7], v20, off offset:2816 nt
	v_and_b32_e32 v20, 0xffff0000, v33
	v_lshlrev_b32_e32 v21, 16, v33
	v_fmaak_f32 v20, v20, v16, 0x4b400000
	v_fmaak_f32 v21, v21, v16, 0x4b400000
	v_perm_b32 v20, v20, v21, s28
	v_and_b32_e32 v21, 0xffff0000, v32
	v_lshlrev_b32_e32 v32, 16, v32
	v_fmaak_f32 v21, v21, v16, 0x4b400000
	v_fmaak_f32 v32, v32, v16, 0x4b400000
	v_perm_b32 v21, v21, v32, s28
	v_perm_b32 v20, v20, v21, s29
	global_store_dword v[6:7], v20, off offset:3072 nt
	v_and_b32_e32 v20, 0xffff0000, v31
	v_lshlrev_b32_e32 v21, 16, v31
	v_fmaak_f32 v20, v20, v16, 0x4b400000
	v_fmaak_f32 v21, v21, v16, 0x4b400000
	v_perm_b32 v20, v20, v21, s28
	v_and_b32_e32 v21, 0xffff0000, v30
	v_lshlrev_b32_e32 v30, 16, v30
	v_fmaak_f32 v21, v21, v16, 0x4b400000
	v_fmaak_f32 v30, v30, v16, 0x4b400000
	v_perm_b32 v21, v21, v30, s28
	v_perm_b32 v20, v20, v21, s29
	global_store_dword v[6:7], v20, off offset:3328 nt
	v_and_b32_e32 v20, 0xffff0000, v29
	v_lshlrev_b32_e32 v21, 16, v29
	v_fmaak_f32 v20, v20, v16, 0x4b400000
	v_fmaak_f32 v21, v21, v16, 0x4b400000
	v_perm_b32 v20, v20, v21, s28
	v_and_b32_e32 v21, 0xffff0000, v28
	v_lshlrev_b32_e32 v28, 16, v28
	v_fmaak_f32 v21, v21, v16, 0x4b400000
	v_fmaak_f32 v28, v28, v16, 0x4b400000
	v_perm_b32 v21, v21, v28, s28
	v_perm_b32 v20, v20, v21, s29
	global_store_dword v[6:7], v20, off offset:3584 nt
	v_and_b32_e32 v20, 0xffff0000, v27
	v_lshlrev_b32_e32 v21, 16, v27
	v_fmaak_f32 v20, v20, v16, 0x4b400000
	v_fmaak_f32 v21, v21, v16, 0x4b400000
	v_perm_b32 v20, v20, v21, s28
	v_and_b32_e32 v21, 0xffff0000, v26
	v_lshlrev_b32_e32 v26, 16, v26
	v_fmaak_f32 v21, v21, v16, 0x4b400000
	v_fmaak_f32 v26, v26, v16, 0x4b400000
	v_perm_b32 v21, v21, v26, s28
	v_perm_b32 v20, v20, v21, s29
	global_store_dword v[6:7], v20, off offset:3840 nt
	v_and_b32_e32 v6, 0xffff0000, v25
	v_lshlrev_b32_e32 v7, 16, v25
	v_fmaak_f32 v6, v6, v16, 0x4b400000
	v_fmaak_f32 v7, v7, v16, 0x4b400000
	v_perm_b32 v6, v6, v7, s28
	v_and_b32_e32 v7, 0xffff0000, v24
	v_lshlrev_b32_e32 v20, 16, v24
	v_fmaak_f32 v7, v7, v16, 0x4b400000
	v_fmaak_f32 v20, v20, v16, 0x4b400000
	v_perm_b32 v7, v7, v20, s28
	v_add_co_u32_e32 v4, vcc, s34, v4
	v_perm_b32 v6, v6, v7, s29
	s_nop 0
	v_addc_co_u32_e32 v5, vcc, 0, v5, vcc
	global_store_dword v[4:5], v6, off nt
	v_and_b32_e32 v6, 0xffff0000, v23
	v_lshlrev_b32_e32 v7, 16, v23
	v_fmaak_f32 v6, v6, v16, 0x4b400000
	v_fmaak_f32 v7, v7, v16, 0x4b400000
	v_perm_b32 v6, v6, v7, s28
	v_and_b32_e32 v7, 0xffff0000, v22
	v_lshlrev_b32_e32 v20, 16, v22
	v_fmaak_f32 v7, v7, v16, 0x4b400000
	v_fmaak_f32 v20, v20, v16, 0x4b400000
	v_perm_b32 v7, v7, v20, s28
	v_perm_b32 v6, v6, v7, s29
	global_store_dword v[4:5], v6, off offset:256 nt
	v_and_b32_e32 v6, 0xffff0000, v97
	v_lshlrev_b32_e32 v7, 16, v97
	v_fmaak_f32 v6, v6, v16, 0x4b400000
	v_fmaak_f32 v7, v7, v16, 0x4b400000
	v_perm_b32 v6, v6, v7, s28
	v_and_b32_e32 v7, 0xffff0000, v96
	v_lshlrev_b32_e32 v20, 16, v96
	v_fmaak_f32 v7, v7, v16, 0x4b400000
	v_fmaak_f32 v20, v20, v16, 0x4b400000
	v_perm_b32 v7, v7, v20, s28
	v_perm_b32 v6, v6, v7, s29
	global_store_dword v[4:5], v6, off offset:512 nt
	v_and_b32_e32 v6, 0xffff0000, v98
	v_lshlrev_b32_e32 v7, 16, v98
	v_fmaak_f32 v6, v6, v16, 0x4b400000
	v_fmaak_f32 v7, v7, v16, 0x4b400000
	v_perm_b32 v6, v6, v7, s28
	v_and_b32_e32 v7, 0xffff0000, v19
	v_lshlrev_b32_e32 v19, 16, v19
	v_fmaak_f32 v7, v7, v16, 0x4b400000
	v_fmaak_f32 v19, v19, v16, 0x4b400000
	v_perm_b32 v7, v7, v19, s28
	v_perm_b32 v6, v6, v7, s29
	global_store_dword v[4:5], v6, off offset:768 nt
	v_and_b32_e32 v6, 0xffff0000, v95
	v_lshlrev_b32_e32 v7, 16, v95
	v_fmaak_f32 v6, v6, v16, 0x4b400000
	v_fmaak_f32 v7, v7, v16, 0x4b400000
	v_perm_b32 v6, v6, v7, s28
	v_and_b32_e32 v7, 0xffff0000, v94
	v_lshlrev_b32_e32 v19, 16, v94
	v_fmaak_f32 v7, v7, v16, 0x4b400000
	v_fmaak_f32 v19, v19, v16, 0x4b400000
	v_perm_b32 v7, v7, v19, s28
	v_perm_b32 v6, v6, v7, s29
	global_store_dword v[4:5], v6, off offset:1024 nt
	v_and_b32_e32 v6, 0xffff0000, v100
	v_lshlrev_b32_e32 v7, 16, v100
	v_fmaak_f32 v6, v6, v16, 0x4b400000
	v_fmaak_f32 v7, v7, v16, 0x4b400000
	v_perm_b32 v6, v6, v7, s28
	v_and_b32_e32 v7, 0xffff0000, v99
	v_lshlrev_b32_e32 v19, 16, v99
	v_fmaak_f32 v7, v7, v16, 0x4b400000
	v_fmaak_f32 v19, v19, v16, 0x4b400000
	v_perm_b32 v7, v7, v19, s28
	v_perm_b32 v6, v6, v7, s29
	global_store_dword v[4:5], v6, off offset:1280 nt
	v_and_b32_e32 v6, 0xffff0000, v101
	v_lshlrev_b32_e32 v7, 16, v101
	v_fmaak_f32 v6, v6, v16, 0x4b400000
	v_fmaak_f32 v7, v7, v16, 0x4b400000
	v_perm_b32 v6, v6, v7, s28
	v_and_b32_e32 v7, 0xffff0000, v18
	v_lshlrev_b32_e32 v18, 16, v18
	v_fmaak_f32 v7, v7, v16, 0x4b400000
	v_fmaak_f32 v18, v18, v16, 0x4b400000
	v_perm_b32 v7, v7, v18, s28
	v_perm_b32 v6, v6, v7, s29
	global_store_dword v[4:5], v6, off offset:1536 nt
	v_and_b32_e32 v6, 0xffff0000, v17
	v_lshlrev_b32_e32 v7, 16, v17
	v_fmaak_f32 v6, v6, v16, 0x4b400000
	v_fmaak_f32 v7, v7, v16, 0x4b400000
	v_perm_b32 v6, v6, v7, s28
	v_and_b32_e32 v7, 0xffff0000, v15
	v_lshlrev_b32_e32 v15, 16, v15
	v_fmaak_f32 v7, v7, v16, 0x4b400000
	v_fmaak_f32 v15, v15, v16, 0x4b400000
	v_perm_b32 v7, v7, v15, s28
	v_perm_b32 v6, v6, v7, s29
	global_store_dword v[4:5], v6, off offset:1792 nt
	v_and_b32_e32 v6, 0xffff0000, v14
	v_lshlrev_b32_e32 v7, 16, v14
	v_fmaak_f32 v6, v6, v16, 0x4b400000
	v_fmaak_f32 v7, v7, v16, 0x4b400000
	v_perm_b32 v6, v6, v7, s28
	v_and_b32_e32 v7, 0xffff0000, v13
	v_lshlrev_b32_e32 v13, 16, v13
	v_fmaak_f32 v7, v7, v16, 0x4b400000
	v_fmaak_f32 v13, v13, v16, 0x4b400000
	v_perm_b32 v7, v7, v13, s28
	v_perm_b32 v6, v6, v7, s29
	global_store_dword v[4:5], v6, off offset:2048 nt
	v_and_b32_e32 v6, 0xffff0000, v11
	v_lshlrev_b32_e32 v7, 16, v11
	v_fmaak_f32 v6, v6, v16, 0x4b400000
	v_fmaak_f32 v7, v7, v16, 0x4b400000
	v_perm_b32 v6, v6, v7, s28
	v_and_b32_e32 v7, 0xffff0000, v9
	v_lshlrev_b32_e32 v9, 16, v9
	v_fmaak_f32 v7, v7, v16, 0x4b400000
	v_fmaak_f32 v9, v9, v16, 0x4b400000
	v_perm_b32 v7, v7, v9, s28
	v_perm_b32 v6, v6, v7, s29
	global_store_dword v[4:5], v6, off offset:2304 nt
	v_and_b32_e32 v6, 0xffff0000, v12
	v_lshlrev_b32_e32 v7, 16, v12
	v_fmaak_f32 v6, v6, v16, 0x4b400000
	v_fmaak_f32 v7, v7, v16, 0x4b400000
	v_perm_b32 v6, v6, v7, s28
	v_and_b32_e32 v7, 0xffff0000, v10
	v_lshlrev_b32_e32 v9, 16, v10
	v_fmaak_f32 v7, v7, v16, 0x4b400000
	v_fmaak_f32 v9, v9, v16, 0x4b400000
	v_perm_b32 v7, v7, v9, s28
	v_perm_b32 v6, v6, v7, s29
	global_store_dword v[4:5], v6, off offset:2560 nt
	s_and_saveexec_b64 s[18:19], s[6:7]
	s_cbranch_execz .LBB0_908
	s_add_u32 s36, s8, s2
	s_addc_u32 s37, s9, s3
	v_mul_f32_e32 v4, 0x3c010204, v8
	global_store_dword v85, v4, s[36:37] nt
	s_branch .LBB0_908
